# MFMA order within each 8-group changed to snake order (one operand changes per step) to cut operand toggling
# baseline (speedup 1.0000x reference)
; #define PG8_STAGE(bufoff, gbase, voff) do { _Pragma("unroll") for (int _i = 0; _i < 2; ++_i) \
;         __builtin_amdgcn_global_load_lds((const unsigned*)((const char*)(gbase) + (voff)[_i]), (LAS unsigned*)(lds + (bufoff) + ldsw + _i * 8192), 16, 0, 0); } while (0)
; #define PG8_LDA(dst, b, h) do { _Pragma("unroll") for (int m = 0; m < 4; ++m) _Pragma("unroll") for (int k = 0; k < 2; ++k) dst[m][k] = *(const LAS bf16x8*)(lds + PG8_SA(b, h) + aoff + m * 2048 + k * 1024); } while (0)
; #define PG8_LDB(dst, b, h) do { _Pragma("unroll") for (int n = 0; n < 2; ++n) _Pragma("unroll") for (int k = 0; k < 2; ++k) dst[n][k] = *(const LAS bf16x8*)(lds + PG8_SB(b, h) + boff + n * 2048 + k * 1024); } while (0)
; #define PG8_MMA(ai, bj, At, Bt) do { __builtin_amdgcn_s_setprio(3); _Pragma("unroll") for (int m = 0; m < 4; ++m) _Pragma("unroll") for (int n = 0; n < 2; ++n) _Pragma("unroll") for (int k = 0; k < 2; ++k) \
;         acc[ai][bj][m][n] = __builtin_amdgcn_mfma_f32_16x16x32_bf16(Bt[n][k], At[m][k], acc[ai][bj][m][n], 0, 0, 0); __builtin_amdgcn_s_setprio(0); } while (0)
; #define PG8_WAIT_V(n) asm volatile("s_waitcnt vmcnt(" #n ")" ::: "memory")
; #define PG8_WAIT_L(n) asm volatile("s_waitcnt lgkmcnt(" #n ")" ::: "memory")
; #define PG8_BAR __builtin_amdgcn_s_barrier()
; #define PG8_SCHED __builtin_amdgcn_sched_barrier(0)
; template <class Epi, class Sched, bool ALIGN_EPI = false, bool SP2 = false>
; __device__ __forceinline__ void gemm_phase(LAS unsigned char* lds, const Gemm g, const Sched& S, const Epi& E) {
;     ...
;             PG8_LDB(B0, 0, 0); PG8_LDB(B1, 0, 1); PG8_SCHED; PG8_LDA(At, 0, 0); PG8_STAGE(PG8_SA(1, 1), a1 + hsA, voffA);
;             PG8_WAIT_V(8); PG8_WAIT_L(0); PG8_BAR; PG8_MMA(0, 0, At, B0); PG8_MMA(0, 1, At, B1); PG8_BAR; PG8_SCHED;
;             PG8_LDA(At, 0, 1); PG8_STAGE(PG8_SB(0, 0), b2, voffB); PG8_STAGE(PG8_SB(0, 1), b2 + hsB, voffB); PG8_STAGE(PG8_SA(0, 0), a2, voffA);
;             PG8_WAIT_V(8); PG8_WAIT_L(0); PG8_BAR; PG8_MMA(1, 0, At, B0); PG8_MMA(1, 1, At, B1); PG8_BAR; PG8_SCHED;
.LBB0_64:
	ds_read_b128 v[128:131], v158
	ds_read_b128 v[150:153], v158 offset:1024
	ds_read_b128 v[166:169], v158 offset:2048
	ds_read_b128 v[170:173], v158 offset:3072
	ds_read_b128 v[174:177], v159
	ds_read_b128 v[178:181], v159 offset:1024
	ds_read_b128 v[182:185], v159 offset:2048
	ds_read_b128 v[186:189], v159 offset:3072
	s_add_u32 s6, s4, 0xffefc080
	s_addc_u32 s7, s5, -1
	s_cmp_eq_u32 s91, 60
	s_cselect_b32 s63, s59, s7
	s_cselect_b32 s62, s58, s6
	s_cselect_b32 s7, s61, s90
	s_cselect_b32 s6, s60, s89
	v_lshl_add_u64 v[226:227], s[4:5], 0, v[142:143]
	s_add_i32 m0, s68, 0xc000
	ds_read_b128 v[190:193], v160
	ds_read_b128 v[194:197], v160 offset:1024
	ds_read_b128 v[198:201], v160 offset:2048
	ds_read_b128 v[206:209], v160 offset:3072
	ds_read_b128 v[210:213], v160 offset:4096
	ds_read_b128 v[214:217], v160 offset:5120
	ds_read_b128 v[218:221], v160 offset:6144
	ds_read_b128 v[222:225], v160 offset:7168
	global_load_lds_dwordx4 v[226:227], off
	v_lshl_add_u64 v[226:227], s[4:5], 0, v[144:145]
	s_add_i32 m0, s68, 0xe000
	s_nop 0
	global_load_lds_dwordx4 v[226:227], off
	s_waitcnt vmcnt(8)
	s_waitcnt lgkmcnt(0)
	s_barrier
	s_setprio 3
	s_waitcnt lgkmcnt(0)
	v_mfma_f32_16x16x32_bf16 v[124:127], v[128:131], v[190:193], v[124:127]
	v_mfma_f32_16x16x32_bf16 v[120:123], v[166:169], v[190:193], v[120:123]
	v_mfma_f32_16x16x32_bf16 v[104:107], v[166:169], v[198:201], v[104:107]
	v_mfma_f32_16x16x32_bf16 v[108:111], v[128:131], v[198:201], v[108:111]
	v_mfma_f32_16x16x32_bf16 v[92:95], v[128:131], v[210:213], v[92:95]
	v_mfma_f32_16x16x32_bf16 v[88:91], v[166:169], v[210:213], v[88:91]
	v_mfma_f32_16x16x32_bf16 v[72:75], v[166:169], v[218:221], v[72:75]
	v_mfma_f32_16x16x32_bf16 v[76:79], v[128:131], v[218:221], v[76:79]
	v_mfma_f32_16x16x32_bf16 v[124:127], v[150:153], v[194:197], v[124:127]
	v_mfma_f32_16x16x32_bf16 v[120:123], v[170:173], v[194:197], v[120:123]
	v_mfma_f32_16x16x32_bf16 v[104:107], v[170:173], v[206:209], v[104:107]
	v_mfma_f32_16x16x32_bf16 v[108:111], v[150:153], v[206:209], v[108:111]
	v_mfma_f32_16x16x32_bf16 v[92:95], v[150:153], v[214:217], v[92:95]
	v_mfma_f32_16x16x32_bf16 v[88:91], v[170:173], v[214:217], v[88:91]
	v_mfma_f32_16x16x32_bf16 v[72:75], v[170:173], v[222:225], v[72:75]
	v_mfma_f32_16x16x32_bf16 v[76:79], v[150:153], v[222:225], v[76:79]
	s_setprio 0
	s_setprio 3
	v_mfma_f32_16x16x32_bf16 v[116:119], v[174:177], v[190:193], v[116:119]
	v_mfma_f32_16x16x32_bf16 v[112:115], v[182:185], v[190:193], v[112:115]
	v_mfma_f32_16x16x32_bf16 v[96:99], v[182:185], v[198:201], v[96:99]
	v_mfma_f32_16x16x32_bf16 v[100:103], v[174:177], v[198:201], v[100:103]
	v_mfma_f32_16x16x32_bf16 v[84:87], v[174:177], v[210:213], v[84:87]
	v_mfma_f32_16x16x32_bf16 v[80:83], v[182:185], v[210:213], v[80:83]
	v_mfma_f32_16x16x32_bf16 v[64:67], v[182:185], v[218:221], v[64:67]
	v_mfma_f32_16x16x32_bf16 v[68:71], v[174:177], v[218:221], v[68:71]
	v_mfma_f32_16x16x32_bf16 v[116:119], v[178:181], v[194:197], v[116:119]
	v_mfma_f32_16x16x32_bf16 v[112:115], v[186:189], v[194:197], v[112:115]
	v_mfma_f32_16x16x32_bf16 v[96:99], v[186:189], v[206:209], v[96:99]
	v_mfma_f32_16x16x32_bf16 v[100:103], v[178:181], v[206:209], v[100:103]
	v_mfma_f32_16x16x32_bf16 v[84:87], v[178:181], v[214:217], v[84:87]
	v_mfma_f32_16x16x32_bf16 v[80:83], v[186:189], v[214:217], v[80:83]
	v_mfma_f32_16x16x32_bf16 v[64:67], v[186:189], v[222:225], v[64:67]
	v_mfma_f32_16x16x32_bf16 v[68:71], v[178:181], v[222:225], v[68:71]
	s_setprio 0
	s_barrier
	s_add_i32 s92, s82, s67
	v_lshl_add_u64 v[226:227], s[6:7], 0, v[134:135]
	s_mov_b32 m0, s92
	ds_read_b128 v[190:193], v160 offset:16384
	ds_read_b128 v[194:197], v160 offset:17408
	ds_read_b128 v[198:201], v160 offset:18432
	ds_read_b128 v[206:209], v160 offset:19456
	ds_read_b128 v[210:213], v160 offset:20480
	ds_read_b128 v[214:217], v160 offset:21504
	ds_read_b128 v[218:221], v160 offset:22528
	ds_read_b128 v[222:225], v160 offset:23552
	global_load_lds_dwordx4 v[226:227], off
	s_add_i32 m0, s92, 0x2000
	s_add_u32 s92, s6, 0x41000
	v_lshl_add_u64 v[228:229], s[6:7], 0, v[138:139]
	s_addc_u32 s93, s7, 0
	s_add_i32 s94, s83, s67
	global_load_lds_dwordx4 v[228:229], off
	v_lshl_add_u64 v[230:231], s[92:93], 0, v[134:135]
	s_mov_b32 m0, s94
	v_lshl_add_u64 v[232:233], s[62:63], 0, v[136:137]
	global_load_lds_dwordx4 v[230:231], off
	v_lshl_add_u64 v[230:231], s[92:93], 0, v[138:139]
	s_add_i32 m0, s94, 0x2000
	s_nop 0
	global_load_lds_dwordx4 v[230:231], off
	v_lshl_add_u64 v[230:231], s[62:63], 0, v[132:133]
	s_mov_b32 m0, s68
	s_nop 0
	global_load_lds_dwordx4 v[230:231], off
	s_mov_b32 m0, s69
	s_nop 0
	global_load_lds_dwordx4 v[232:233], off
	s_waitcnt vmcnt(8)
	s_waitcnt lgkmcnt(0)
	s_barrier
; #define PG8_STAGE(bufoff, gbase, voff) do { _Pragma("unroll") for (int _i = 0; _i < 2; ++_i) \
;         __builtin_amdgcn_global_load_lds((const unsigned*)((const char*)(gbase) + (voff)[_i]), (LAS unsigned*)(lds + (bufoff) + ldsw + _i * 8192), 16, 0, 0); } while (0)
; #define PG8_LDA(dst, b, h) do { _Pragma("unroll") for (int m = 0; m < 4; ++m) _Pragma("unroll") for (int k = 0; k < 2; ++k) dst[m][k] = *(const LAS bf16x8*)(lds + PG8_SA(b, h) + aoff + m * 2048 + k * 1024); } while (0)
; #define PG8_LDB(dst, b, h) do { _Pragma("unroll") for (int n = 0; n < 2; ++n) _Pragma("unroll") for (int k = 0; k < 2; ++k) dst[n][k] = *(const LAS bf16x8*)(lds + PG8_SB(b, h) + boff + n * 2048 + k * 1024); } while (0)
; #define PG8_MMA(ai, bj, At, Bt) do { __builtin_amdgcn_s_setprio(3); _Pragma("unroll") for (int m = 0; m < 4; ++m) _Pragma("unroll") for (int n = 0; n < 2; ++n) _Pragma("unroll") for (int k = 0; k < 2; ++k) \
;         acc[ai][bj][m][n] = __builtin_amdgcn_mfma_f32_16x16x32_bf16(Bt[n][k], At[m][k], acc[ai][bj][m][n], 0, 0, 0); __builtin_amdgcn_s_setprio(0); } while (0)
; #define PG8_WAIT_V(n) asm volatile("s_waitcnt vmcnt(" #n ")" ::: "memory")
; #define PG8_WAIT_L(n) asm volatile("s_waitcnt lgkmcnt(" #n ")" ::: "memory")
; #define PG8_BAR __builtin_amdgcn_s_barrier()
; #define PG8_SCHED __builtin_amdgcn_sched_barrier(0)
; template <class Epi, class Sched, bool ALIGN_EPI = false, bool SP2 = false>
; __device__ __forceinline__ void gemm_phase(LAS unsigned char* lds, const Gemm g, const Sched& S, const Epi& E) {
;     ...
;             PG8_WAIT_V(8); PG8_WAIT_L(0); PG8_BAR; PG8_MMA(1, 0, At, B0); PG8_MMA(1, 1, At, B1); PG8_BAR; PG8_SCHED;
;             PG8_LDB(B0, 1, 0); PG8_LDB(B1, 1, 1); PG8_SCHED; PG8_LDA(At, 1, 0); PG8_STAGE(PG8_SA(0, 1), a2 + hsA, voffA);
;             PG8_WAIT_V(8); PG8_WAIT_L(0); PG8_BAR; PG8_MMA(0, 0, At, B0); PG8_MMA(0, 1, At, B1); PG8_BAR; PG8_SCHED;
	s_setprio 3
	s_waitcnt lgkmcnt(0)
	v_mfma_f32_16x16x32_bf16 v[60:63], v[128:131], v[190:193], v[60:63]
	v_mfma_f32_16x16x32_bf16 v[56:59], v[166:169], v[190:193], v[56:59]
	v_mfma_f32_16x16x32_bf16 v[40:43], v[166:169], v[198:201], v[40:43]
	v_mfma_f32_16x16x32_bf16 v[44:47], v[128:131], v[198:201], v[44:47]
	v_mfma_f32_16x16x32_bf16 v[28:31], v[128:131], v[210:213], v[28:31]
	v_mfma_f32_16x16x32_bf16 v[24:27], v[166:169], v[210:213], v[24:27]
	v_mfma_f32_16x16x32_bf16 v[8:11], v[166:169], v[218:221], v[8:11]
	v_mfma_f32_16x16x32_bf16 v[12:15], v[128:131], v[218:221], v[12:15]
	v_mfma_f32_16x16x32_bf16 v[60:63], v[150:153], v[194:197], v[60:63]
	v_mfma_f32_16x16x32_bf16 v[56:59], v[170:173], v[194:197], v[56:59]
	v_mfma_f32_16x16x32_bf16 v[40:43], v[170:173], v[206:209], v[40:43]
	v_mfma_f32_16x16x32_bf16 v[44:47], v[150:153], v[206:209], v[44:47]
	v_mfma_f32_16x16x32_bf16 v[28:31], v[150:153], v[214:217], v[28:31]
	v_mfma_f32_16x16x32_bf16 v[24:27], v[170:173], v[214:217], v[24:27]
	v_mfma_f32_16x16x32_bf16 v[8:11], v[170:173], v[222:225], v[8:11]
	v_mfma_f32_16x16x32_bf16 v[12:15], v[150:153], v[222:225], v[12:15]
	s_setprio 0
	s_setprio 3
	v_mfma_f32_16x16x32_bf16 v[52:55], v[174:177], v[190:193], v[52:55]
	v_mfma_f32_16x16x32_bf16 v[48:51], v[182:185], v[190:193], v[48:51]
	v_mfma_f32_16x16x32_bf16 v[32:35], v[182:185], v[198:201], v[32:35]
	v_mfma_f32_16x16x32_bf16 v[36:39], v[174:177], v[198:201], v[36:39]
	v_mfma_f32_16x16x32_bf16 v[20:23], v[174:177], v[210:213], v[20:23]
	v_mfma_f32_16x16x32_bf16 v[16:19], v[182:185], v[210:213], v[16:19]
	v_mfma_f32_16x16x32_bf16 v[0:3], v[182:185], v[218:221], v[0:3]
	v_mfma_f32_16x16x32_bf16 v[4:7], v[174:177], v[218:221], v[4:7]
	v_mfma_f32_16x16x32_bf16 v[52:55], v[178:181], v[194:197], v[52:55]
	v_mfma_f32_16x16x32_bf16 v[48:51], v[186:189], v[194:197], v[48:51]
	v_mfma_f32_16x16x32_bf16 v[32:35], v[186:189], v[206:209], v[32:35]
	v_mfma_f32_16x16x32_bf16 v[36:39], v[178:181], v[206:209], v[36:39]
	v_mfma_f32_16x16x32_bf16 v[20:23], v[178:181], v[214:217], v[20:23]
	v_mfma_f32_16x16x32_bf16 v[16:19], v[186:189], v[214:217], v[16:19]
	v_mfma_f32_16x16x32_bf16 v[0:3], v[186:189], v[222:225], v[0:3]
	v_mfma_f32_16x16x32_bf16 v[4:7], v[178:181], v[222:225], v[4:7]
	s_setprio 0
	s_barrier
	s_add_i32 s92, 0, 0x18000
	v_add_u32_e32 v165, s92, v156
	s_add_i32 s93, 0, 0x1c000
	ds_read_b128 v[128:131], v165
	ds_read_b128 v[150:153], v165 offset:1024
	ds_read_b128 v[166:169], v165 offset:2048
	ds_read_b128 v[170:173], v165 offset:3072
	v_add_u32_e32 v165, s93, v156
	ds_read_b128 v[174:177], v165
	ds_read_b128 v[178:181], v165 offset:1024
	ds_read_b128 v[182:185], v165 offset:2048
	ds_read_b128 v[186:189], v165 offset:3072
	s_add_u32 s62, s62, 0x104000
	s_addc_u32 s63, s63, 0
	s_mov_b32 m0, s70
	v_lshl_add_u64 v[234:235], s[62:63], 0, v[132:133]
	ds_read_b128 v[190:193], v160 offset:32768
	ds_read_b128 v[194:197], v160 offset:33792
	ds_read_b128 v[198:201], v160 offset:34816
	ds_read_b128 v[206:209], v160 offset:35840
	ds_read_b128 v[210:213], v160 offset:36864
	ds_read_b128 v[214:217], v160 offset:37888
	ds_read_b128 v[218:221], v160 offset:38912
	ds_read_b128 v[222:225], v160 offset:39936
	global_load_lds_dwordx4 v[234:235], off
	v_lshl_add_u64 v[234:235], s[62:63], 0, v[136:137]
	s_mov_b32 m0, s71
	s_nop 0
	global_load_lds_dwordx4 v[234:235], off
	s_waitcnt vmcnt(8)
	s_waitcnt lgkmcnt(0)
	s_barrier
	s_setprio 3
	s_waitcnt lgkmcnt(0)
	v_mfma_f32_16x16x32_bf16 v[124:127], v[128:131], v[190:193], v[124:127]
	v_mfma_f32_16x16x32_bf16 v[120:123], v[166:169], v[190:193], v[120:123]
	v_mfma_f32_16x16x32_bf16 v[104:107], v[166:169], v[198:201], v[104:107]
	v_mfma_f32_16x16x32_bf16 v[108:111], v[128:131], v[198:201], v[108:111]
	v_mfma_f32_16x16x32_bf16 v[92:95], v[128:131], v[210:213], v[92:95]
	v_mfma_f32_16x16x32_bf16 v[88:91], v[166:169], v[210:213], v[88:91]
	v_mfma_f32_16x16x32_bf16 v[72:75], v[166:169], v[218:221], v[72:75]
	v_mfma_f32_16x16x32_bf16 v[76:79], v[128:131], v[218:221], v[76:79]
	v_mfma_f32_16x16x32_bf16 v[124:127], v[150:153], v[194:197], v[124:127]
	v_mfma_f32_16x16x32_bf16 v[120:123], v[170:173], v[194:197], v[120:123]
	v_mfma_f32_16x16x32_bf16 v[104:107], v[170:173], v[206:209], v[104:107]
	v_mfma_f32_16x16x32_bf16 v[108:111], v[150:153], v[206:209], v[108:111]
	v_mfma_f32_16x16x32_bf16 v[92:95], v[150:153], v[214:217], v[92:95]
	v_mfma_f32_16x16x32_bf16 v[88:91], v[170:173], v[214:217], v[88:91]
	v_mfma_f32_16x16x32_bf16 v[72:75], v[170:173], v[222:225], v[72:75]
	v_mfma_f32_16x16x32_bf16 v[76:79], v[150:153], v[222:225], v[76:79]
	s_setprio 0
	s_setprio 3
	v_mfma_f32_16x16x32_bf16 v[116:119], v[174:177], v[190:193], v[116:119]
	v_mfma_f32_16x16x32_bf16 v[112:115], v[182:185], v[190:193], v[112:115]
	v_mfma_f32_16x16x32_bf16 v[96:99], v[182:185], v[198:201], v[96:99]
	v_mfma_f32_16x16x32_bf16 v[100:103], v[174:177], v[198:201], v[100:103]
	v_mfma_f32_16x16x32_bf16 v[84:87], v[174:177], v[210:213], v[84:87]
	v_mfma_f32_16x16x32_bf16 v[80:83], v[182:185], v[210:213], v[80:83]
	v_mfma_f32_16x16x32_bf16 v[64:67], v[182:185], v[218:221], v[64:67]
	v_mfma_f32_16x16x32_bf16 v[68:71], v[174:177], v[218:221], v[68:71]
	v_mfma_f32_16x16x32_bf16 v[116:119], v[178:181], v[194:197], v[116:119]
	v_mfma_f32_16x16x32_bf16 v[112:115], v[186:189], v[194:197], v[112:115]
	v_mfma_f32_16x16x32_bf16 v[96:99], v[186:189], v[206:209], v[96:99]
	v_mfma_f32_16x16x32_bf16 v[100:103], v[178:181], v[206:209], v[100:103]
	v_mfma_f32_16x16x32_bf16 v[84:87], v[178:181], v[214:217], v[84:87]
	v_mfma_f32_16x16x32_bf16 v[80:83], v[186:189], v[214:217], v[80:83]
	v_mfma_f32_16x16x32_bf16 v[64:67], v[186:189], v[222:225], v[64:67]
	v_mfma_f32_16x16x32_bf16 v[68:71], v[178:181], v[222:225], v[68:71]
	s_setprio 0
	s_barrier
; #define PG8_STAGE(bufoff, gbase, voff) do { _Pragma("unroll") for (int _i = 0; _i < 2; ++_i) \
;         __builtin_amdgcn_global_load_lds((const unsigned*)((const char*)(gbase) + (voff)[_i]), (LAS unsigned*)(lds + (bufoff) + ldsw + _i * 8192), 16, 0, 0); } while (0)
; #define PG8_LDA(dst, b, h) do { _Pragma("unroll") for (int m = 0; m < 4; ++m) _Pragma("unroll") for (int k = 0; k < 2; ++k) dst[m][k] = *(const LAS bf16x8*)(lds + PG8_SA(b, h) + aoff + m * 2048 + k * 1024); } while (0)
; #define PG8_MMA(ai, bj, At, Bt) do { __builtin_amdgcn_s_setprio(3); _Pragma("unroll") for (int m = 0; m < 4; ++m) _Pragma("unroll") for (int n = 0; n < 2; ++n) _Pragma("unroll") for (int k = 0; k < 2; ++k) \
;         acc[ai][bj][m][n] = __builtin_amdgcn_mfma_f32_16x16x32_bf16(Bt[n][k], At[m][k], acc[ai][bj][m][n], 0, 0, 0); __builtin_amdgcn_s_setprio(0); } while (0)
; #define PG8_WAIT_V(n) asm volatile("s_waitcnt vmcnt(" #n ")" ::: "memory")
; #define PG8_WAIT_L(n) asm volatile("s_waitcnt lgkmcnt(" #n ")" ::: "memory")
; #define PG8_BAR __builtin_amdgcn_s_barrier()
; #define PG8_SCHED __builtin_amdgcn_sched_barrier(0)
; template <class Epi, class Sched, bool ALIGN_EPI = false, bool SP2 = false>
; __device__ __forceinline__ void gemm_phase(LAS unsigned char* lds, const Gemm g, const Sched& S, const Epi& E) {
;     ...
;             PG8_LDA(At, 1, 1); PG8_STAGE(PG8_SB(1, 0), b3, voffB); PG8_STAGE(PG8_SB(1, 1), b3 + hsB, voffB); PG8_STAGE(PG8_SA(1, 0), a3, voffA);
;             PG8_WAIT_V(8); PG8_WAIT_L(0); PG8_BAR; PG8_MMA(1, 0, At, B0); PG8_MMA(1, 1, At, B1); PG8_BAR; PG8_SCHED;
	s_add_i32 s62, s92, s67
	v_lshl_add_u64 v[226:227], v[226:227], 0, s[46:47]
	s_mov_b32 m0, s62
	ds_read_b128 v[190:193], v160 offset:49152
	ds_read_b128 v[194:197], v160 offset:50176
	ds_read_b128 v[198:201], v160 offset:51200
	ds_read_b128 v[206:209], v160 offset:52224
	ds_read_b128 v[210:213], v160 offset:53248
	ds_read_b128 v[214:217], v160 offset:54272
	ds_read_b128 v[218:221], v160 offset:55296
	ds_read_b128 v[222:225], v160 offset:56320
	global_load_lds_dwordx4 v[226:227], off
	s_add_i32 m0, s62, 0x2000
	s_add_u32 s6, s6, 0x41080
	v_lshl_add_u64 v[226:227], v[228:229], 0, s[46:47]
	s_addc_u32 s7, s7, 0
	s_add_i32 s62, s93, s67
	global_load_lds_dwordx4 v[226:227], off
	v_lshl_add_u64 v[226:227], s[6:7], 0, v[134:135]
	s_mov_b32 m0, s62
	s_nop 0
	global_load_lds_dwordx4 v[226:227], off
	v_lshl_add_u64 v[226:227], s[6:7], 0, v[138:139]
	s_add_i32 m0, s62, 0x2000
	s_nop 0
	global_load_lds_dwordx4 v[226:227], off
	v_lshl_add_u64 v[226:227], v[230:231], 0, s[46:47]
	s_mov_b32 m0, s76
	s_nop 0
	global_load_lds_dwordx4 v[226:227], off
	v_lshl_add_u64 v[226:227], v[232:233], 0, s[46:47]
	s_mov_b32 m0, s77
	s_nop 0
	global_load_lds_dwordx4 v[226:227], off
	s_waitcnt vmcnt(8)
	s_waitcnt lgkmcnt(0)
	s_barrier
	s_setprio 3
	s_waitcnt lgkmcnt(0)
	v_mfma_f32_16x16x32_bf16 v[60:63], v[128:131], v[190:193], v[60:63]
	v_mfma_f32_16x16x32_bf16 v[56:59], v[166:169], v[190:193], v[56:59]
	v_mfma_f32_16x16x32_bf16 v[40:43], v[166:169], v[198:201], v[40:43]
	v_mfma_f32_16x16x32_bf16 v[44:47], v[128:131], v[198:201], v[44:47]
	v_mfma_f32_16x16x32_bf16 v[28:31], v[128:131], v[210:213], v[28:31]
	v_mfma_f32_16x16x32_bf16 v[24:27], v[166:169], v[210:213], v[24:27]
	v_mfma_f32_16x16x32_bf16 v[8:11], v[166:169], v[218:221], v[8:11]
	v_mfma_f32_16x16x32_bf16 v[12:15], v[128:131], v[218:221], v[12:15]
	v_mfma_f32_16x16x32_bf16 v[60:63], v[150:153], v[194:197], v[60:63]
	v_mfma_f32_16x16x32_bf16 v[56:59], v[170:173], v[194:197], v[56:59]
	v_mfma_f32_16x16x32_bf16 v[40:43], v[170:173], v[206:209], v[40:43]
	v_mfma_f32_16x16x32_bf16 v[44:47], v[150:153], v[206:209], v[44:47]
	v_mfma_f32_16x16x32_bf16 v[28:31], v[150:153], v[214:217], v[28:31]
	v_mfma_f32_16x16x32_bf16 v[24:27], v[170:173], v[214:217], v[24:27]
	v_mfma_f32_16x16x32_bf16 v[8:11], v[170:173], v[222:225], v[8:11]
	v_mfma_f32_16x16x32_bf16 v[12:15], v[150:153], v[222:225], v[12:15]
	s_setprio 0
	s_setprio 3
	v_mfma_f32_16x16x32_bf16 v[52:55], v[174:177], v[190:193], v[52:55]
	v_mfma_f32_16x16x32_bf16 v[48:51], v[182:185], v[190:193], v[48:51]
	v_mfma_f32_16x16x32_bf16 v[32:35], v[182:185], v[198:201], v[32:35]
	v_mfma_f32_16x16x32_bf16 v[36:39], v[174:177], v[198:201], v[36:39]
	v_mfma_f32_16x16x32_bf16 v[20:23], v[174:177], v[210:213], v[20:23]
	v_mfma_f32_16x16x32_bf16 v[16:19], v[182:185], v[210:213], v[16:19]
	v_mfma_f32_16x16x32_bf16 v[0:3], v[182:185], v[218:221], v[0:3]
	v_mfma_f32_16x16x32_bf16 v[4:7], v[174:177], v[218:221], v[4:7]
	v_mfma_f32_16x16x32_bf16 v[52:55], v[178:181], v[194:197], v[52:55]
	v_mfma_f32_16x16x32_bf16 v[48:51], v[186:189], v[194:197], v[48:51]
	v_mfma_f32_16x16x32_bf16 v[32:35], v[186:189], v[206:209], v[32:35]
	v_mfma_f32_16x16x32_bf16 v[36:39], v[178:181], v[206:209], v[36:39]
	v_mfma_f32_16x16x32_bf16 v[20:23], v[178:181], v[214:217], v[20:23]
	v_mfma_f32_16x16x32_bf16 v[16:19], v[186:189], v[214:217], v[16:19]
	v_mfma_f32_16x16x32_bf16 v[0:3], v[186:189], v[222:225], v[0:3]
	v_mfma_f32_16x16x32_bf16 v[4:7], v[178:181], v[222:225], v[4:7]
	s_setprio 0
	s_barrier
	s_add_i32 s91, s91, 2
	s_add_u32 s4, s4, 0x100
	s_addc_u32 s5, s5, 0
	s_add_u32 s89, s89, 0x100
	s_addc_u32 s90, s90, 0
	s_cmp_gt_u32 s91, 61
	s_cbranch_scc0 .LBB0_64
	s_and_b64 vcc, exec, s[50:51]
	s_cbranch_vccz .LBB0_67
	s_barrier

; #define PG8_STAGE(bufoff, gbase, voff) do { _Pragma("unroll") for (int _i = 0; _i < 2; ++_i) \
;         __builtin_amdgcn_global_load_lds((const unsigned*)((const char*)(gbase) + (voff)[_i]), (LAS unsigned*)(lds + (bufoff) + ldsw + _i * 8192), 16, 0, 0); } while (0)
; #define PG8_LDA(dst, b, h) do { _Pragma("unroll") for (int m = 0; m < 4; ++m) _Pragma("unroll") for (int k = 0; k < 2; ++k) dst[m][k] = *(const LAS bf16x8*)(lds + PG8_SA(b, h) + aoff + m * 2048 + k * 1024); } while (0)
; #define PG8_LDB(dst, b, h) do { _Pragma("unroll") for (int n = 0; n < 2; ++n) _Pragma("unroll") for (int k = 0; k < 2; ++k) dst[n][k] = *(const LAS bf16x8*)(lds + PG8_SB(b, h) + boff + n * 2048 + k * 1024); } while (0)
; #define PG8_MMA(ai, bj, At, Bt) do { __builtin_amdgcn_s_setprio(3); _Pragma("unroll") for (int m = 0; m < 4; ++m) _Pragma("unroll") for (int n = 0; n < 2; ++n) _Pragma("unroll") for (int k = 0; k < 2; ++k) \
;         acc[ai][bj][m][n] = __builtin_amdgcn_mfma_f32_16x16x32_bf16(Bt[n][k], At[m][k], acc[ai][bj][m][n], 0, 0, 0); __builtin_amdgcn_s_setprio(0); } while (0)
; #define PG8_WAIT_V(n) asm volatile("s_waitcnt vmcnt(" #n ")" ::: "memory")
; #define PG8_WAIT_L(n) asm volatile("s_waitcnt lgkmcnt(" #n ")" ::: "memory")
; #define PG8_BAR __builtin_amdgcn_s_barrier()
; #define PG8_SCHED __builtin_amdgcn_sched_barrier(0)
; template <class Epi, class Sched, bool ALIGN_EPI = false, bool SP2 = false>
; __device__ __forceinline__ void gemm_phase(LAS unsigned char* lds, const Gemm g, const Sched& S, const Epi& E) {
;     ...
;             PG8_LDB(B0, 0, 0); PG8_LDB(B1, 0, 1); PG8_SCHED; PG8_LDA(At, 0, 0); PG8_STAGE(PG8_SA(1, 1), a1 + hsA, voffA);
;             PG8_WAIT_V(8); PG8_WAIT_L(0); PG8_BAR; PG8_MMA(0, 0, At, B0); PG8_MMA(0, 1, At, B1); PG8_BAR; PG8_SCHED;
;             PG8_LDA(At, 0, 1); PG8_STAGE(PG8_SB(0, 0), b2, voffB); PG8_STAGE(PG8_SB(0, 1), b2 + hsB, voffB); PG8_STAGE(PG8_SA(0, 0), a2, voffA);
;             PG8_WAIT_V(8); PG8_WAIT_L(0); PG8_BAR; PG8_MMA(1, 0, At, B0); PG8_MMA(1, 1, At, B1); PG8_BAR; PG8_SCHED;
.LBB0_234:
	v_add_u32_e32 v1, s88, v194
	ds_read_b128 v[84:87], v1
	ds_read_b128 v[96:99], v1 offset:1024
	ds_read_b128 v[140:143], v1 offset:2048
	ds_read_b128 v[144:147], v1 offset:3072
	v_add_u32_e32 v1, s89, v194
	s_add_u32 s4, s64, s66
	ds_read_b128 v[152:155], v1
	ds_read_b128 v[156:159], v1 offset:1024
	ds_read_b128 v[160:163], v1 offset:2048
	ds_read_b128 v[182:185], v1 offset:3072
	s_addc_u32 s5, s65, s67
	s_add_u32 s4, s4, 0x100
	s_addc_u32 s5, s5, 0
	s_add_u32 s96, s93, s66
	s_addc_u32 s97, s94, s67
	s_cmpk_eq_i32 s66, 0x1f00
	s_cselect_b32 s9, s59, s5
	s_cselect_b32 s8, s91, s4
	s_cselect_b32 s5, s61, s97
	s_cselect_b32 s4, s60, s96
	v_lshl_add_u64 v[2:3], v[148:149], 0, s[66:67]
	s_add_i32 m0, s41, 0xc000
	ds_read_b128 v[186:189], v198
	ds_read_b128 v[208:211], v198 offset:1024
	ds_read_b128 v[212:215], v198 offset:2048
	ds_read_b128 v[216:219], v198 offset:3072
	ds_read_b128 v[220:223], v198 offset:4096
	ds_read_b128 v[224:227], v198 offset:5120
	ds_read_b128 v[228:231], v198 offset:6144
	ds_read_b128 v[232:235], v198 offset:7168
	global_load_lds_dwordx4 v[2:3], off
	v_lshl_add_u64 v[2:3], v[150:151], 0, s[66:67]
	s_add_i32 m0, s41, 0xe000
	s_nop 0
	global_load_lds_dwordx4 v[2:3], off
	s_waitcnt vmcnt(8)
	s_waitcnt lgkmcnt(0)
	s_barrier
	s_setprio 3
	s_waitcnt lgkmcnt(0)
	v_mfma_f32_16x16x32_bf16 v[136:139], v[84:87], v[186:189], v[136:139]
	v_mfma_f32_16x16x32_bf16 v[132:135], v[140:143], v[186:189], v[132:135]
	v_mfma_f32_16x16x32_bf16 v[116:119], v[140:143], v[212:215], v[116:119]
	v_mfma_f32_16x16x32_bf16 v[120:123], v[84:87], v[212:215], v[120:123]
	v_mfma_f32_16x16x32_bf16 v[104:107], v[84:87], v[220:223], v[104:107]
	v_mfma_f32_16x16x32_bf16 v[100:103], v[140:143], v[220:223], v[100:103]
	v_mfma_f32_16x16x32_bf16 v[76:79], v[140:143], v[228:231], v[76:79]
	v_mfma_f32_16x16x32_bf16 v[80:83], v[84:87], v[228:231], v[80:83]
	v_mfma_f32_16x16x32_bf16 v[136:139], v[96:99], v[208:211], v[136:139]
	v_mfma_f32_16x16x32_bf16 v[132:135], v[144:147], v[208:211], v[132:135]
	v_mfma_f32_16x16x32_bf16 v[116:119], v[144:147], v[216:219], v[116:119]
	v_mfma_f32_16x16x32_bf16 v[120:123], v[96:99], v[216:219], v[120:123]
	v_mfma_f32_16x16x32_bf16 v[104:107], v[96:99], v[224:227], v[104:107]
	v_mfma_f32_16x16x32_bf16 v[100:103], v[144:147], v[224:227], v[100:103]
	v_mfma_f32_16x16x32_bf16 v[76:79], v[144:147], v[232:235], v[76:79]
	v_mfma_f32_16x16x32_bf16 v[80:83], v[96:99], v[232:235], v[80:83]
	s_setprio 0
	s_setprio 3
	v_mfma_f32_16x16x32_bf16 v[128:131], v[152:155], v[186:189], v[128:131]
	v_mfma_f32_16x16x32_bf16 v[124:127], v[160:163], v[186:189], v[124:127]
	v_mfma_f32_16x16x32_bf16 v[108:111], v[160:163], v[212:215], v[108:111]
	v_mfma_f32_16x16x32_bf16 v[112:115], v[152:155], v[212:215], v[112:115]
	v_mfma_f32_16x16x32_bf16 v[92:95], v[152:155], v[220:223], v[92:95]
	v_mfma_f32_16x16x32_bf16 v[88:91], v[160:163], v[220:223], v[88:91]
	v_mfma_f32_16x16x32_bf16 v[68:71], v[160:163], v[228:231], v[68:71]
	v_mfma_f32_16x16x32_bf16 v[72:75], v[152:155], v[228:231], v[72:75]
	v_mfma_f32_16x16x32_bf16 v[128:131], v[156:159], v[208:211], v[128:131]
	v_mfma_f32_16x16x32_bf16 v[124:127], v[182:185], v[208:211], v[124:127]
	v_mfma_f32_16x16x32_bf16 v[108:111], v[182:185], v[216:219], v[108:111]
	v_mfma_f32_16x16x32_bf16 v[112:115], v[156:159], v[216:219], v[112:115]
	v_mfma_f32_16x16x32_bf16 v[92:95], v[156:159], v[224:227], v[92:95]
	v_mfma_f32_16x16x32_bf16 v[88:91], v[182:185], v[224:227], v[88:91]
	v_mfma_f32_16x16x32_bf16 v[68:71], v[182:185], v[232:235], v[68:71]
	v_mfma_f32_16x16x32_bf16 v[72:75], v[156:159], v[232:235], v[72:75]
	s_setprio 0
	s_barrier
	s_add_i32 s96, s88, s31
	v_lshl_add_u64 v[190:191], s[4:5], 0, v[166:167]
	s_mov_b32 m0, s96
	ds_read_b128 v[186:189], v198 offset:16384
	ds_read_b128 v[208:211], v198 offset:17408
	ds_read_b128 v[212:215], v198 offset:18432
	ds_read_b128 v[216:219], v198 offset:19456
	ds_read_b128 v[220:223], v198 offset:20480
	ds_read_b128 v[224:227], v198 offset:21504
	ds_read_b128 v[228:231], v198 offset:22528
	ds_read_b128 v[232:235], v198 offset:23552
	global_load_lds_dwordx4 v[190:191], off
	s_add_i32 m0, s96, 0x2000
	s_add_u32 s96, s4, 0x104000
	v_lshl_add_u64 v[236:237], s[4:5], 0, v[170:171]
	s_addc_u32 s97, s5, 0
	s_add_i32 s98, s89, s31
	global_load_lds_dwordx4 v[236:237], off
	v_lshl_add_u64 v[2:3], s[96:97], 0, v[166:167]
	s_mov_b32 m0, s98
	v_lshl_add_u64 v[238:239], s[8:9], 0, v[164:165]
	global_load_lds_dwordx4 v[2:3], off
	v_lshl_add_u64 v[2:3], s[96:97], 0, v[170:171]
	s_add_i32 m0, s98, 0x2000
	v_lshl_add_u64 v[240:241], s[8:9], 0, v[168:169]
	global_load_lds_dwordx4 v[2:3], off
	s_mov_b32 m0, s41
	s_nop 0
	global_load_lds_dwordx4 v[238:239], off
	s_mov_b32 m0, s68
	s_nop 0
	global_load_lds_dwordx4 v[240:241], off
	s_waitcnt vmcnt(8)
	s_waitcnt lgkmcnt(0)
	s_barrier
; #define PG8_STAGE(bufoff, gbase, voff) do { _Pragma("unroll") for (int _i = 0; _i < 2; ++_i) \
;         __builtin_amdgcn_global_load_lds((const unsigned*)((const char*)(gbase) + (voff)[_i]), (LAS unsigned*)(lds + (bufoff) + ldsw + _i * 8192), 16, 0, 0); } while (0)
; #define PG8_LDA(dst, b, h) do { _Pragma("unroll") for (int m = 0; m < 4; ++m) _Pragma("unroll") for (int k = 0; k < 2; ++k) dst[m][k] = *(const LAS bf16x8*)(lds + PG8_SA(b, h) + aoff + m * 2048 + k * 1024); } while (0)
; #define PG8_LDB(dst, b, h) do { _Pragma("unroll") for (int n = 0; n < 2; ++n) _Pragma("unroll") for (int k = 0; k < 2; ++k) dst[n][k] = *(const LAS bf16x8*)(lds + PG8_SB(b, h) + boff + n * 2048 + k * 1024); } while (0)
; #define PG8_MMA(ai, bj, At, Bt) do { __builtin_amdgcn_s_setprio(3); _Pragma("unroll") for (int m = 0; m < 4; ++m) _Pragma("unroll") for (int n = 0; n < 2; ++n) _Pragma("unroll") for (int k = 0; k < 2; ++k) \
;         acc[ai][bj][m][n] = __builtin_amdgcn_mfma_f32_16x16x32_bf16(Bt[n][k], At[m][k], acc[ai][bj][m][n], 0, 0, 0); __builtin_amdgcn_s_setprio(0); } while (0)
; #define PG8_WAIT_V(n) asm volatile("s_waitcnt vmcnt(" #n ")" ::: "memory")
; #define PG8_WAIT_L(n) asm volatile("s_waitcnt lgkmcnt(" #n ")" ::: "memory")
; #define PG8_BAR __builtin_amdgcn_s_barrier()
; #define PG8_SCHED __builtin_amdgcn_sched_barrier(0)
; template <class Epi, class Sched, bool ALIGN_EPI = false, bool SP2 = false>
; __device__ __forceinline__ void gemm_phase(LAS unsigned char* lds, const Gemm g, const Sched& S, const Epi& E) {
;     ...
;             PG8_WAIT_V(8); PG8_WAIT_L(0); PG8_BAR; PG8_MMA(1, 0, At, B0); PG8_MMA(1, 1, At, B1); PG8_BAR; PG8_SCHED;
;             PG8_LDB(B0, 1, 0); PG8_LDB(B1, 1, 1); PG8_SCHED; PG8_LDA(At, 1, 0); PG8_STAGE(PG8_SA(0, 1), a2 + hsA, voffA);
;             PG8_WAIT_V(8); PG8_WAIT_L(0); PG8_BAR; PG8_MMA(0, 0, At, B0); PG8_MMA(0, 1, At, B1); PG8_BAR; PG8_SCHED;
	s_setprio 3
	s_waitcnt lgkmcnt(0)
	v_mfma_f32_16x16x32_bf16 v[64:67], v[84:87], v[186:189], v[64:67]
	v_mfma_f32_16x16x32_bf16 v[60:63], v[140:143], v[186:189], v[60:63]
	v_mfma_f32_16x16x32_bf16 v[44:47], v[140:143], v[212:215], v[44:47]
	v_mfma_f32_16x16x32_bf16 v[48:51], v[84:87], v[212:215], v[48:51]
	v_mfma_f32_16x16x32_bf16 v[32:35], v[84:87], v[220:223], v[32:35]
	v_mfma_f32_16x16x32_bf16 v[28:31], v[140:143], v[220:223], v[28:31]
	v_mfma_f32_16x16x32_bf16 v[12:15], v[140:143], v[228:231], v[12:15]
	v_mfma_f32_16x16x32_bf16 v[16:19], v[84:87], v[228:231], v[16:19]
	v_mfma_f32_16x16x32_bf16 v[64:67], v[96:99], v[208:211], v[64:67]
	v_mfma_f32_16x16x32_bf16 v[60:63], v[144:147], v[208:211], v[60:63]
	v_mfma_f32_16x16x32_bf16 v[44:47], v[144:147], v[216:219], v[44:47]
	v_mfma_f32_16x16x32_bf16 v[48:51], v[96:99], v[216:219], v[48:51]
	v_mfma_f32_16x16x32_bf16 v[32:35], v[96:99], v[224:227], v[32:35]
	v_mfma_f32_16x16x32_bf16 v[28:31], v[144:147], v[224:227], v[28:31]
	v_mfma_f32_16x16x32_bf16 v[12:15], v[144:147], v[232:235], v[12:15]
	v_mfma_f32_16x16x32_bf16 v[16:19], v[96:99], v[232:235], v[16:19]
	s_setprio 0
	s_setprio 3
	v_mfma_f32_16x16x32_bf16 v[56:59], v[152:155], v[186:189], v[56:59]
	v_mfma_f32_16x16x32_bf16 v[52:55], v[160:163], v[186:189], v[52:55]
	v_mfma_f32_16x16x32_bf16 v[36:39], v[160:163], v[212:215], v[36:39]
	v_mfma_f32_16x16x32_bf16 v[40:43], v[152:155], v[212:215], v[40:43]
	v_mfma_f32_16x16x32_bf16 v[24:27], v[152:155], v[220:223], v[24:27]
	v_mfma_f32_16x16x32_bf16 v[20:23], v[160:163], v[220:223], v[20:23]
	v_mfma_f32_16x16x32_bf16 v[2:5], v[160:163], v[228:231], v[4:7]
	v_mfma_f32_16x16x32_bf16 v[8:11], v[152:155], v[228:231], v[8:11]
	v_mfma_f32_16x16x32_bf16 v[56:59], v[156:159], v[208:211], v[56:59]
	v_mfma_f32_16x16x32_bf16 v[52:55], v[182:185], v[208:211], v[52:55]
	v_mfma_f32_16x16x32_bf16 v[36:39], v[182:185], v[216:219], v[36:39]
	v_mfma_f32_16x16x32_bf16 v[40:43], v[156:159], v[216:219], v[40:43]
	v_mfma_f32_16x16x32_bf16 v[24:27], v[156:159], v[224:227], v[24:27]
	v_mfma_f32_16x16x32_bf16 v[20:23], v[182:185], v[224:227], v[20:23]
	v_mfma_f32_16x16x32_bf16 v[2:5], v[182:185], v[232:235], v[2:5]
	v_mfma_f32_16x16x32_bf16 v[8:11], v[156:159], v[232:235], v[8:11]
	s_setprio 0
	s_barrier
	s_add_i32 s96, 0, 0x18000
	v_add_u32_e32 v1, s96, v194
	s_add_i32 s97, 0, 0x1c000
	ds_read_b128 v[84:87], v1
	ds_read_b128 v[96:99], v1 offset:1024
	ds_read_b128 v[140:143], v1 offset:2048
	ds_read_b128 v[144:147], v1 offset:3072
	v_add_u32_e32 v1, s97, v194
	ds_read_b128 v[152:155], v1
	ds_read_b128 v[156:159], v1 offset:1024
	ds_read_b128 v[160:163], v1 offset:2048
	ds_read_b128 v[182:185], v1 offset:3072
	s_add_u32 s8, s8, 0x100000
	s_addc_u32 s9, s9, 0
	s_mov_b32 m0, s69
	v_lshl_add_u64 v[6:7], s[8:9], 0, v[164:165]
	ds_read_b128 v[186:189], v198 offset:32768
	ds_read_b128 v[208:211], v198 offset:33792
	ds_read_b128 v[212:215], v198 offset:34816
	ds_read_b128 v[216:219], v198 offset:35840
	ds_read_b128 v[220:223], v198 offset:36864
	ds_read_b128 v[224:227], v198 offset:37888
	ds_read_b128 v[228:231], v198 offset:38912
	ds_read_b128 v[232:235], v198 offset:39936
	global_load_lds_dwordx4 v[6:7], off
	v_lshl_add_u64 v[6:7], s[8:9], 0, v[168:169]
	s_mov_b32 m0, s70
	s_nop 0
	global_load_lds_dwordx4 v[6:7], off
	s_waitcnt vmcnt(8)
	s_waitcnt lgkmcnt(0)
	s_barrier
	s_setprio 3
	s_waitcnt lgkmcnt(0)
	v_mfma_f32_16x16x32_bf16 v[136:139], v[84:87], v[186:189], v[136:139]
	v_mfma_f32_16x16x32_bf16 v[132:135], v[140:143], v[186:189], v[132:135]
	v_mfma_f32_16x16x32_bf16 v[116:119], v[140:143], v[212:215], v[116:119]
	v_mfma_f32_16x16x32_bf16 v[120:123], v[84:87], v[212:215], v[120:123]
	v_mfma_f32_16x16x32_bf16 v[104:107], v[84:87], v[220:223], v[104:107]
	v_mfma_f32_16x16x32_bf16 v[100:103], v[140:143], v[220:223], v[100:103]
	v_mfma_f32_16x16x32_bf16 v[76:79], v[140:143], v[228:231], v[76:79]
	v_mfma_f32_16x16x32_bf16 v[80:83], v[84:87], v[228:231], v[80:83]
	v_mfma_f32_16x16x32_bf16 v[136:139], v[96:99], v[208:211], v[136:139]
	v_mfma_f32_16x16x32_bf16 v[132:135], v[144:147], v[208:211], v[132:135]
	v_mfma_f32_16x16x32_bf16 v[116:119], v[144:147], v[216:219], v[116:119]
	v_mfma_f32_16x16x32_bf16 v[120:123], v[96:99], v[216:219], v[120:123]
	v_mfma_f32_16x16x32_bf16 v[104:107], v[96:99], v[224:227], v[104:107]
	v_mfma_f32_16x16x32_bf16 v[100:103], v[144:147], v[224:227], v[100:103]
	v_mfma_f32_16x16x32_bf16 v[76:79], v[144:147], v[232:235], v[76:79]
	v_mfma_f32_16x16x32_bf16 v[80:83], v[96:99], v[232:235], v[80:83]
	s_setprio 0
	s_setprio 3
	v_mfma_f32_16x16x32_bf16 v[128:131], v[152:155], v[186:189], v[128:131]
	v_mfma_f32_16x16x32_bf16 v[124:127], v[160:163], v[186:189], v[124:127]
	v_mfma_f32_16x16x32_bf16 v[108:111], v[160:163], v[212:215], v[108:111]
	v_mfma_f32_16x16x32_bf16 v[112:115], v[152:155], v[212:215], v[112:115]
	v_mfma_f32_16x16x32_bf16 v[92:95], v[152:155], v[220:223], v[92:95]
	v_mfma_f32_16x16x32_bf16 v[88:91], v[160:163], v[220:223], v[88:91]
	v_mfma_f32_16x16x32_bf16 v[68:71], v[160:163], v[228:231], v[68:71]
	v_mfma_f32_16x16x32_bf16 v[72:75], v[152:155], v[228:231], v[72:75]
	v_mfma_f32_16x16x32_bf16 v[128:131], v[156:159], v[208:211], v[128:131]
	v_mfma_f32_16x16x32_bf16 v[124:127], v[182:185], v[208:211], v[124:127]
	v_mfma_f32_16x16x32_bf16 v[108:111], v[182:185], v[216:219], v[108:111]
	v_mfma_f32_16x16x32_bf16 v[112:115], v[156:159], v[216:219], v[112:115]
	v_mfma_f32_16x16x32_bf16 v[92:95], v[156:159], v[224:227], v[92:95]
	v_mfma_f32_16x16x32_bf16 v[88:91], v[182:185], v[224:227], v[88:91]
	v_mfma_f32_16x16x32_bf16 v[68:71], v[182:185], v[232:235], v[68:71]
	v_mfma_f32_16x16x32_bf16 v[72:75], v[156:159], v[232:235], v[72:75]
	s_setprio 0
	s_barrier
; #define PG8_STAGE(bufoff, gbase, voff) do { _Pragma("unroll") for (int _i = 0; _i < 2; ++_i) \
;         __builtin_amdgcn_global_load_lds((const unsigned*)((const char*)(gbase) + (voff)[_i]), (LAS unsigned*)(lds + (bufoff) + ldsw + _i * 8192), 16, 0, 0); } while (0)
; #define PG8_LDA(dst, b, h) do { _Pragma("unroll") for (int m = 0; m < 4; ++m) _Pragma("unroll") for (int k = 0; k < 2; ++k) dst[m][k] = *(const LAS bf16x8*)(lds + PG8_SA(b, h) + aoff + m * 2048 + k * 1024); } while (0)
; #define PG8_MMA(ai, bj, At, Bt) do { __builtin_amdgcn_s_setprio(3); _Pragma("unroll") for (int m = 0; m < 4; ++m) _Pragma("unroll") for (int n = 0; n < 2; ++n) _Pragma("unroll") for (int k = 0; k < 2; ++k) \
;         acc[ai][bj][m][n] = __builtin_amdgcn_mfma_f32_16x16x32_bf16(Bt[n][k], At[m][k], acc[ai][bj][m][n], 0, 0, 0); __builtin_amdgcn_s_setprio(0); } while (0)
; #define PG8_WAIT_V(n) asm volatile("s_waitcnt vmcnt(" #n ")" ::: "memory")
; #define PG8_WAIT_L(n) asm volatile("s_waitcnt lgkmcnt(" #n ")" ::: "memory")
; #define PG8_BAR __builtin_amdgcn_s_barrier()
; #define PG8_SCHED __builtin_amdgcn_sched_barrier(0)
; template <class Epi, class Sched, bool ALIGN_EPI = false, bool SP2 = false>
; __device__ __forceinline__ void gemm_phase(LAS unsigned char* lds, const Gemm g, const Sched& S, const Epi& E) {
;     ...
;             PG8_LDA(At, 1, 1); PG8_STAGE(PG8_SB(1, 0), b3, voffB); PG8_STAGE(PG8_SB(1, 1), b3 + hsB, voffB); PG8_STAGE(PG8_SA(1, 0), a3, voffA);
;             PG8_WAIT_V(8); PG8_WAIT_L(0); PG8_BAR; PG8_MMA(1, 0, At, B0); PG8_MMA(1, 1, At, B1); PG8_BAR; PG8_SCHED;
	s_add_i32 s8, s96, s31
	v_lshl_add_u64 v[6:7], v[190:191], 0, s[24:25]
	s_mov_b32 m0, s8
	ds_read_b128 v[186:189], v198 offset:49152
	ds_read_b128 v[208:211], v198 offset:50176
	ds_read_b128 v[212:215], v198 offset:51200
	ds_read_b128 v[216:219], v198 offset:52224
	ds_read_b128 v[220:223], v198 offset:53248
	ds_read_b128 v[224:227], v198 offset:54272
	ds_read_b128 v[228:231], v198 offset:55296
	ds_read_b128 v[232:235], v198 offset:56320
	global_load_lds_dwordx4 v[6:7], off
	s_add_i32 m0, s8, 0x2000
	s_add_u32 s4, s4, 0x104080
	v_lshl_add_u64 v[6:7], v[236:237], 0, s[24:25]
	s_addc_u32 s5, s5, 0
	s_add_i32 s8, s97, s31
	global_load_lds_dwordx4 v[6:7], off
	v_lshl_add_u64 v[6:7], s[4:5], 0, v[166:167]
	s_mov_b32 m0, s8
	s_nop 0
	global_load_lds_dwordx4 v[6:7], off
	v_lshl_add_u64 v[6:7], s[4:5], 0, v[170:171]
	s_add_i32 m0, s8, 0x2000
	s_nop 0
	global_load_lds_dwordx4 v[6:7], off
	v_lshl_add_u64 v[6:7], v[238:239], 0, s[24:25]
	s_mov_b32 m0, s81
	s_nop 0
	global_load_lds_dwordx4 v[6:7], off
	v_lshl_add_u64 v[6:7], v[240:241], 0, s[24:25]
	s_mov_b32 m0, s82
	s_nop 0
	global_load_lds_dwordx4 v[6:7], off
	s_waitcnt vmcnt(8)
	s_waitcnt lgkmcnt(0)
	s_barrier
	s_setprio 3
	s_waitcnt lgkmcnt(0)
	v_mfma_f32_16x16x32_bf16 v[64:67], v[84:87], v[186:189], v[64:67]
	v_mfma_f32_16x16x32_bf16 v[60:63], v[140:143], v[186:189], v[60:63]
	v_mfma_f32_16x16x32_bf16 v[44:47], v[140:143], v[212:215], v[44:47]
	v_mfma_f32_16x16x32_bf16 v[48:51], v[84:87], v[212:215], v[48:51]
	v_mfma_f32_16x16x32_bf16 v[32:35], v[84:87], v[220:223], v[32:35]
	v_mfma_f32_16x16x32_bf16 v[28:31], v[140:143], v[220:223], v[28:31]
	v_mfma_f32_16x16x32_bf16 v[12:15], v[140:143], v[228:231], v[12:15]
	v_mfma_f32_16x16x32_bf16 v[16:19], v[84:87], v[228:231], v[16:19]
	v_mfma_f32_16x16x32_bf16 v[64:67], v[96:99], v[208:211], v[64:67]
	v_mfma_f32_16x16x32_bf16 v[60:63], v[144:147], v[208:211], v[60:63]
	v_mfma_f32_16x16x32_bf16 v[44:47], v[144:147], v[216:219], v[44:47]
	v_mfma_f32_16x16x32_bf16 v[48:51], v[96:99], v[216:219], v[48:51]
	v_mfma_f32_16x16x32_bf16 v[32:35], v[96:99], v[224:227], v[32:35]
	v_mfma_f32_16x16x32_bf16 v[28:31], v[144:147], v[224:227], v[28:31]
	v_mfma_f32_16x16x32_bf16 v[12:15], v[144:147], v[232:235], v[12:15]
	v_mfma_f32_16x16x32_bf16 v[16:19], v[96:99], v[232:235], v[16:19]
	s_setprio 0
	s_setprio 3
	v_mfma_f32_16x16x32_bf16 v[56:59], v[152:155], v[186:189], v[56:59]
	v_mfma_f32_16x16x32_bf16 v[52:55], v[160:163], v[186:189], v[52:55]
	v_mfma_f32_16x16x32_bf16 v[36:39], v[160:163], v[212:215], v[36:39]
	v_mfma_f32_16x16x32_bf16 v[40:43], v[152:155], v[212:215], v[40:43]
	v_mfma_f32_16x16x32_bf16 v[24:27], v[152:155], v[220:223], v[24:27]
	v_mfma_f32_16x16x32_bf16 v[20:23], v[160:163], v[220:223], v[20:23]
	v_mfma_f32_16x16x32_bf16 v[2:5], v[160:163], v[228:231], v[2:5]
	v_mfma_f32_16x16x32_bf16 v[6:9], v[152:155], v[228:231], v[8:11]
	v_mfma_f32_16x16x32_bf16 v[56:59], v[156:159], v[208:211], v[56:59]
	v_mfma_f32_16x16x32_bf16 v[52:55], v[182:185], v[208:211], v[52:55]
	v_mfma_f32_16x16x32_bf16 v[36:39], v[182:185], v[216:219], v[36:39]
	v_mfma_f32_16x16x32_bf16 v[40:43], v[156:159], v[216:219], v[40:43]
	v_mfma_f32_16x16x32_bf16 v[24:27], v[156:159], v[224:227], v[24:27]
	v_mfma_f32_16x16x32_bf16 v[20:23], v[182:185], v[224:227], v[20:23]
	v_mfma_f32_16x16x32_bf16 v[4:7], v[182:185], v[232:235], v[2:5]
	v_mfma_f32_16x16x32_bf16 v[8:11], v[156:159], v[232:235], v[6:9]
	s_setprio 0
	s_barrier
	s_add_i32 s95, s95, 2
	s_add_u32 s66, s66, 0x100
	s_addc_u32 s67, s67, 0
	s_cmp_gt_u32 s95, 61
	s_cbranch_scc1 .LBB0_237

; #define PG8_STAGE(bufoff, gbase, voff) do { _Pragma("unroll") for (int _i = 0; _i < 2; ++_i) \
;         __builtin_amdgcn_global_load_lds((const unsigned*)((const char*)(gbase) + (voff)[_i]), (LAS unsigned*)(lds + (bufoff) + ldsw + _i * 8192), 16, 0, 0); } while (0)
; #define PG8_LDA(dst, b, h) do { _Pragma("unroll") for (int m = 0; m < 4; ++m) _Pragma("unroll") for (int k = 0; k < 2; ++k) dst[m][k] = *(const LAS bf16x8*)(lds + PG8_SA(b, h) + aoff + m * 2048 + k * 1024); } while (0)
; #define PG8_LDB(dst, b, h) do { _Pragma("unroll") for (int n = 0; n < 2; ++n) _Pragma("unroll") for (int k = 0; k < 2; ++k) dst[n][k] = *(const LAS bf16x8*)(lds + PG8_SB(b, h) + boff + n * 2048 + k * 1024); } while (0)
; #define PG8_MMA(ai, bj, At, Bt) do { __builtin_amdgcn_s_setprio(3); _Pragma("unroll") for (int m = 0; m < 4; ++m) _Pragma("unroll") for (int n = 0; n < 2; ++n) _Pragma("unroll") for (int k = 0; k < 2; ++k) \
;         acc[ai][bj][m][n] = __builtin_amdgcn_mfma_f32_16x16x32_bf16(Bt[n][k], At[m][k], acc[ai][bj][m][n], 0, 0, 0); __builtin_amdgcn_s_setprio(0); } while (0)
; #define PG8_WAIT_V(n) asm volatile("s_waitcnt vmcnt(" #n ")" ::: "memory")
; #define PG8_WAIT_L(n) asm volatile("s_waitcnt lgkmcnt(" #n ")" ::: "memory")
; #define PG8_BAR __builtin_amdgcn_s_barrier()
; #define PG8_SCHED __builtin_amdgcn_sched_barrier(0)
; template <class Epi, class Sched, bool ALIGN_EPI = false, bool SP2 = false>
; __device__ __forceinline__ void gemm_phase(LAS unsigned char* lds, const Gemm g, const Sched& S, const Epi& E) {
;     ...
;             PG8_LDB(B0, 0, 0); PG8_LDB(B1, 0, 1); PG8_SCHED; PG8_LDA(At, 0, 0); PG8_STAGE(PG8_SA(1, 1), a1 + hsA, voffA);
;             PG8_WAIT_V(8); PG8_WAIT_L(0); PG8_BAR; PG8_MMA(0, 0, At, B0); PG8_MMA(0, 1, At, B1); PG8_BAR; PG8_SCHED;
;             PG8_LDA(At, 0, 1); PG8_STAGE(PG8_SB(0, 0), b2, voffB); PG8_STAGE(PG8_SB(0, 1), b2 + hsB, voffB); PG8_STAGE(PG8_SA(0, 0), a2, voffA);
;             PG8_WAIT_V(8); PG8_WAIT_L(0); PG8_BAR; PG8_MMA(1, 0, At, B0); PG8_MMA(1, 1, At, B1); PG8_BAR; PG8_SCHED;
.LBB0_309:
	ds_read_b128 v[112:115], v175
	ds_read_b128 v[132:135], v175 offset:1024
	ds_read_b128 v[136:139], v175 offset:2048
	ds_read_b128 v[140:143], v175 offset:3072
	ds_read_b128 v[144:147], v176
	ds_read_b128 v[148:151], v176 offset:1024
	ds_read_b128 v[184:187], v176 offset:2048
	ds_read_b128 v[188:191], v176 offset:3072
	s_add_u32 s24, s4, 0xffefc080
	s_addc_u32 s25, s5, -1
	s_cmp_eq_u32 s73, 60
	s_cselect_b32 s27, s11, s25
	s_cselect_b32 s26, s10, s24
	s_cselect_b32 s25, s21, s72
	s_cselect_b32 s24, s20, s71
	v_lshl_add_u64 v[200:201], s[4:5], 0, v[164:165]
	s_add_i32 m0, s36, 0xc000
	ds_read_b128 v[192:195], v177
	ds_read_b128 v[196:199], v177 offset:1024
	ds_read_b128 v[206:209], v177 offset:2048
	ds_read_b128 v[210:213], v177 offset:3072
	ds_read_b128 v[214:217], v177 offset:4096
	ds_read_b128 v[218:221], v177 offset:5120
	ds_read_b128 v[222:225], v177 offset:6144
	ds_read_b128 v[226:229], v177 offset:7168
	global_load_lds_dwordx4 v[200:201], off
	v_lshl_add_u64 v[200:201], s[4:5], 0, v[166:167]
	s_add_i32 m0, s36, 0xe000
	s_nop 0
	global_load_lds_dwordx4 v[200:201], off
	s_waitcnt vmcnt(8)
	s_waitcnt lgkmcnt(0)
	s_barrier
	s_setprio 3
	s_waitcnt lgkmcnt(0)
	v_mfma_f32_16x16x32_bf16 v[128:131], v[112:115], v[192:195], v[128:131]
	v_mfma_f32_16x16x32_bf16 v[124:127], v[136:139], v[192:195], v[124:127]
	v_mfma_f32_16x16x32_bf16 v[104:107], v[136:139], v[206:209], v[104:107]
	v_mfma_f32_16x16x32_bf16 v[108:111], v[112:115], v[206:209], v[108:111]
	v_mfma_f32_16x16x32_bf16 v[92:95], v[112:115], v[214:217], v[92:95]
	v_mfma_f32_16x16x32_bf16 v[88:91], v[136:139], v[214:217], v[88:91]
	v_mfma_f32_16x16x32_bf16 v[72:75], v[136:139], v[222:225], v[72:75]
	v_mfma_f32_16x16x32_bf16 v[76:79], v[112:115], v[222:225], v[76:79]
	v_mfma_f32_16x16x32_bf16 v[128:131], v[132:135], v[196:199], v[128:131]
	v_mfma_f32_16x16x32_bf16 v[124:127], v[140:143], v[196:199], v[124:127]
	v_mfma_f32_16x16x32_bf16 v[104:107], v[140:143], v[210:213], v[104:107]
	v_mfma_f32_16x16x32_bf16 v[108:111], v[132:135], v[210:213], v[108:111]
	v_mfma_f32_16x16x32_bf16 v[92:95], v[132:135], v[218:221], v[92:95]
	v_mfma_f32_16x16x32_bf16 v[88:91], v[140:143], v[218:221], v[88:91]
	v_mfma_f32_16x16x32_bf16 v[72:75], v[140:143], v[226:229], v[72:75]
	v_mfma_f32_16x16x32_bf16 v[76:79], v[132:135], v[226:229], v[76:79]
	s_setprio 0
	s_setprio 3
	v_mfma_f32_16x16x32_bf16 v[120:123], v[144:147], v[192:195], v[120:123]
	v_mfma_f32_16x16x32_bf16 v[116:119], v[184:187], v[192:195], v[116:119]
	v_mfma_f32_16x16x32_bf16 v[96:99], v[184:187], v[206:209], v[96:99]
	v_mfma_f32_16x16x32_bf16 v[100:103], v[144:147], v[206:209], v[100:103]
	v_mfma_f32_16x16x32_bf16 v[84:87], v[144:147], v[214:217], v[84:87]
	v_mfma_f32_16x16x32_bf16 v[80:83], v[184:187], v[214:217], v[80:83]
	v_mfma_f32_16x16x32_bf16 v[64:67], v[184:187], v[222:225], v[64:67]
	v_mfma_f32_16x16x32_bf16 v[68:71], v[144:147], v[222:225], v[68:71]
	v_mfma_f32_16x16x32_bf16 v[120:123], v[148:151], v[196:199], v[120:123]
	v_mfma_f32_16x16x32_bf16 v[116:119], v[188:191], v[196:199], v[116:119]
	v_mfma_f32_16x16x32_bf16 v[96:99], v[188:191], v[210:213], v[96:99]
	v_mfma_f32_16x16x32_bf16 v[100:103], v[148:151], v[210:213], v[100:103]
	v_mfma_f32_16x16x32_bf16 v[84:87], v[148:151], v[218:221], v[84:87]
	v_mfma_f32_16x16x32_bf16 v[80:83], v[188:191], v[218:221], v[80:83]
	v_mfma_f32_16x16x32_bf16 v[64:67], v[188:191], v[226:229], v[64:67]
	v_mfma_f32_16x16x32_bf16 v[68:71], v[148:151], v[226:229], v[68:71]
	s_setprio 0
	s_barrier
	s_add_i32 s74, s45, s31
	v_lshl_add_u64 v[200:201], s[24:25], 0, v[154:155]
	s_mov_b32 m0, s74
	ds_read_b128 v[192:195], v177 offset:16384
	ds_read_b128 v[196:199], v177 offset:17408
	ds_read_b128 v[206:209], v177 offset:18432
	ds_read_b128 v[210:213], v177 offset:19456
	ds_read_b128 v[214:217], v177 offset:20480
	ds_read_b128 v[218:221], v177 offset:21504
	ds_read_b128 v[222:225], v177 offset:22528
	ds_read_b128 v[226:229], v177 offset:23552
	global_load_lds_dwordx4 v[200:201], off
	s_add_i32 m0, s74, 0x2000
	s_add_u32 s74, s24, 0x41000
	v_lshl_add_u64 v[230:231], s[24:25], 0, v[158:159]
	s_addc_u32 s75, s25, 0
	s_add_i32 s78, s46, s31
	global_load_lds_dwordx4 v[230:231], off
	v_lshl_add_u64 v[232:233], s[74:75], 0, v[154:155]
	s_mov_b32 m0, s78
	v_lshl_add_u64 v[234:235], s[26:27], 0, v[156:157]
	global_load_lds_dwordx4 v[232:233], off
	v_lshl_add_u64 v[232:233], s[74:75], 0, v[158:159]
	s_add_i32 m0, s78, 0x2000
	s_nop 0
	global_load_lds_dwordx4 v[232:233], off
	v_lshl_add_u64 v[232:233], s[26:27], 0, v[152:153]
	s_mov_b32 m0, s36
	s_nop 0
	global_load_lds_dwordx4 v[232:233], off
	s_mov_b32 m0, s37
	s_nop 0
	global_load_lds_dwordx4 v[234:235], off
	s_waitcnt vmcnt(8)
	s_waitcnt lgkmcnt(0)
	s_barrier
; #define PG8_STAGE(bufoff, gbase, voff) do { _Pragma("unroll") for (int _i = 0; _i < 2; ++_i) \
;         __builtin_amdgcn_global_load_lds((const unsigned*)((const char*)(gbase) + (voff)[_i]), (LAS unsigned*)(lds + (bufoff) + ldsw + _i * 8192), 16, 0, 0); } while (0)
; #define PG8_LDA(dst, b, h) do { _Pragma("unroll") for (int m = 0; m < 4; ++m) _Pragma("unroll") for (int k = 0; k < 2; ++k) dst[m][k] = *(const LAS bf16x8*)(lds + PG8_SA(b, h) + aoff + m * 2048 + k * 1024); } while (0)
; #define PG8_LDB(dst, b, h) do { _Pragma("unroll") for (int n = 0; n < 2; ++n) _Pragma("unroll") for (int k = 0; k < 2; ++k) dst[n][k] = *(const LAS bf16x8*)(lds + PG8_SB(b, h) + boff + n * 2048 + k * 1024); } while (0)
; #define PG8_MMA(ai, bj, At, Bt) do { __builtin_amdgcn_s_setprio(3); _Pragma("unroll") for (int m = 0; m < 4; ++m) _Pragma("unroll") for (int n = 0; n < 2; ++n) _Pragma("unroll") for (int k = 0; k < 2; ++k) \
;         acc[ai][bj][m][n] = __builtin_amdgcn_mfma_f32_16x16x32_bf16(Bt[n][k], At[m][k], acc[ai][bj][m][n], 0, 0, 0); __builtin_amdgcn_s_setprio(0); } while (0)
; #define PG8_WAIT_V(n) asm volatile("s_waitcnt vmcnt(" #n ")" ::: "memory")
; #define PG8_WAIT_L(n) asm volatile("s_waitcnt lgkmcnt(" #n ")" ::: "memory")
; #define PG8_BAR __builtin_amdgcn_s_barrier()
; #define PG8_SCHED __builtin_amdgcn_sched_barrier(0)
; template <class Epi, class Sched, bool ALIGN_EPI = false, bool SP2 = false>
; __device__ __forceinline__ void gemm_phase(LAS unsigned char* lds, const Gemm g, const Sched& S, const Epi& E) {
;     ...
;             PG8_WAIT_V(8); PG8_WAIT_L(0); PG8_BAR; PG8_MMA(1, 0, At, B0); PG8_MMA(1, 1, At, B1); PG8_BAR; PG8_SCHED;
;             PG8_LDB(B0, 1, 0); PG8_LDB(B1, 1, 1); PG8_SCHED; PG8_LDA(At, 1, 0); PG8_STAGE(PG8_SA(0, 1), a2 + hsA, voffA);
;             PG8_WAIT_V(8); PG8_WAIT_L(0); PG8_BAR; PG8_MMA(0, 0, At, B0); PG8_MMA(0, 1, At, B1); PG8_BAR; PG8_SCHED;
	s_setprio 3
	s_waitcnt lgkmcnt(0)
	v_mfma_f32_16x16x32_bf16 v[60:63], v[112:115], v[192:195], v[60:63]
	v_mfma_f32_16x16x32_bf16 v[56:59], v[136:139], v[192:195], v[56:59]
	v_mfma_f32_16x16x32_bf16 v[40:43], v[136:139], v[206:209], v[40:43]
	v_mfma_f32_16x16x32_bf16 v[44:47], v[112:115], v[206:209], v[44:47]
	v_mfma_f32_16x16x32_bf16 v[28:31], v[112:115], v[214:217], v[28:31]
	v_mfma_f32_16x16x32_bf16 v[24:27], v[136:139], v[214:217], v[24:27]
	v_mfma_f32_16x16x32_bf16 v[8:11], v[136:139], v[222:225], v[8:11]
	v_mfma_f32_16x16x32_bf16 v[12:15], v[112:115], v[222:225], v[12:15]
	v_mfma_f32_16x16x32_bf16 v[60:63], v[132:135], v[196:199], v[60:63]
	v_mfma_f32_16x16x32_bf16 v[56:59], v[140:143], v[196:199], v[56:59]
	v_mfma_f32_16x16x32_bf16 v[40:43], v[140:143], v[210:213], v[40:43]
	v_mfma_f32_16x16x32_bf16 v[44:47], v[132:135], v[210:213], v[44:47]
	v_mfma_f32_16x16x32_bf16 v[28:31], v[132:135], v[218:221], v[28:31]
	v_mfma_f32_16x16x32_bf16 v[24:27], v[140:143], v[218:221], v[24:27]
	v_mfma_f32_16x16x32_bf16 v[8:11], v[140:143], v[226:229], v[8:11]
	v_mfma_f32_16x16x32_bf16 v[12:15], v[132:135], v[226:229], v[12:15]
	s_setprio 0
	s_setprio 3
	v_mfma_f32_16x16x32_bf16 v[52:55], v[144:147], v[192:195], v[52:55]
	v_mfma_f32_16x16x32_bf16 v[48:51], v[184:187], v[192:195], v[48:51]
	v_mfma_f32_16x16x32_bf16 v[32:35], v[184:187], v[206:209], v[32:35]
	v_mfma_f32_16x16x32_bf16 v[36:39], v[144:147], v[206:209], v[36:39]
	v_mfma_f32_16x16x32_bf16 v[20:23], v[144:147], v[214:217], v[20:23]
	v_mfma_f32_16x16x32_bf16 v[16:19], v[184:187], v[214:217], v[16:19]
	v_mfma_f32_16x16x32_bf16 v[0:3], v[184:187], v[222:225], v[0:3]
	v_mfma_f32_16x16x32_bf16 v[4:7], v[144:147], v[222:225], v[4:7]
	v_mfma_f32_16x16x32_bf16 v[52:55], v[148:151], v[196:199], v[52:55]
	v_mfma_f32_16x16x32_bf16 v[48:51], v[188:191], v[196:199], v[48:51]
	v_mfma_f32_16x16x32_bf16 v[32:35], v[188:191], v[210:213], v[32:35]
	v_mfma_f32_16x16x32_bf16 v[36:39], v[148:151], v[210:213], v[36:39]
	v_mfma_f32_16x16x32_bf16 v[20:23], v[148:151], v[218:221], v[20:23]
	v_mfma_f32_16x16x32_bf16 v[16:19], v[188:191], v[218:221], v[16:19]
	v_mfma_f32_16x16x32_bf16 v[0:3], v[188:191], v[226:229], v[0:3]
	v_mfma_f32_16x16x32_bf16 v[4:7], v[148:151], v[226:229], v[4:7]
	s_setprio 0
	s_barrier
	s_add_i32 s74, 0, 0x18000
	s_add_i32 s75, 0, 0x1c000
	v_add_u32_e32 v140, s74, v173
	v_add_u32_e32 v188, s75, v173
	ds_read_b128 v[112:115], v140
	ds_read_b128 v[132:135], v140 offset:1024
	ds_read_b128 v[136:139], v140 offset:2048
	ds_read_b128 v[140:143], v140 offset:3072
	ds_read_b128 v[144:147], v188
	ds_read_b128 v[148:151], v188 offset:1024
	ds_read_b128 v[184:187], v188 offset:2048
	ds_read_b128 v[188:191], v188 offset:3072
	s_add_u32 s26, s26, 0x104000
	s_addc_u32 s27, s27, 0
	s_mov_b32 m0, s38
	v_lshl_add_u64 v[236:237], s[26:27], 0, v[152:153]
	ds_read_b128 v[192:195], v177 offset:32768
	ds_read_b128 v[196:199], v177 offset:33792
	ds_read_b128 v[206:209], v177 offset:34816
	ds_read_b128 v[210:213], v177 offset:35840
	ds_read_b128 v[214:217], v177 offset:36864
	ds_read_b128 v[218:221], v177 offset:37888
	ds_read_b128 v[222:225], v177 offset:38912
	ds_read_b128 v[226:229], v177 offset:39936
	global_load_lds_dwordx4 v[236:237], off
	v_lshl_add_u64 v[236:237], s[26:27], 0, v[156:157]
	s_mov_b32 m0, s39
	s_nop 0
	global_load_lds_dwordx4 v[236:237], off
	s_waitcnt vmcnt(8)
	s_waitcnt lgkmcnt(0)
	s_barrier
	s_setprio 3
	s_waitcnt lgkmcnt(0)
	v_mfma_f32_16x16x32_bf16 v[128:131], v[112:115], v[192:195], v[128:131]
	v_mfma_f32_16x16x32_bf16 v[124:127], v[136:139], v[192:195], v[124:127]
	v_mfma_f32_16x16x32_bf16 v[104:107], v[136:139], v[206:209], v[104:107]
	v_mfma_f32_16x16x32_bf16 v[108:111], v[112:115], v[206:209], v[108:111]
	v_mfma_f32_16x16x32_bf16 v[92:95], v[112:115], v[214:217], v[92:95]
	v_mfma_f32_16x16x32_bf16 v[88:91], v[136:139], v[214:217], v[88:91]
	v_mfma_f32_16x16x32_bf16 v[72:75], v[136:139], v[222:225], v[72:75]
	v_mfma_f32_16x16x32_bf16 v[76:79], v[112:115], v[222:225], v[76:79]
	v_mfma_f32_16x16x32_bf16 v[128:131], v[132:135], v[196:199], v[128:131]
	v_mfma_f32_16x16x32_bf16 v[124:127], v[140:143], v[196:199], v[124:127]
	v_mfma_f32_16x16x32_bf16 v[104:107], v[140:143], v[210:213], v[104:107]
	v_mfma_f32_16x16x32_bf16 v[108:111], v[132:135], v[210:213], v[108:111]
	v_mfma_f32_16x16x32_bf16 v[92:95], v[132:135], v[218:221], v[92:95]
	v_mfma_f32_16x16x32_bf16 v[88:91], v[140:143], v[218:221], v[88:91]
	v_mfma_f32_16x16x32_bf16 v[72:75], v[140:143], v[226:229], v[72:75]
	v_mfma_f32_16x16x32_bf16 v[76:79], v[132:135], v[226:229], v[76:79]
	s_setprio 0
	s_setprio 3
	v_mfma_f32_16x16x32_bf16 v[120:123], v[144:147], v[192:195], v[120:123]
	v_mfma_f32_16x16x32_bf16 v[116:119], v[184:187], v[192:195], v[116:119]
	v_mfma_f32_16x16x32_bf16 v[96:99], v[184:187], v[206:209], v[96:99]
	v_mfma_f32_16x16x32_bf16 v[100:103], v[144:147], v[206:209], v[100:103]
	v_mfma_f32_16x16x32_bf16 v[84:87], v[144:147], v[214:217], v[84:87]
	v_mfma_f32_16x16x32_bf16 v[80:83], v[184:187], v[214:217], v[80:83]
	v_mfma_f32_16x16x32_bf16 v[64:67], v[184:187], v[222:225], v[64:67]
	v_mfma_f32_16x16x32_bf16 v[68:71], v[144:147], v[222:225], v[68:71]
	v_mfma_f32_16x16x32_bf16 v[120:123], v[148:151], v[196:199], v[120:123]
	v_mfma_f32_16x16x32_bf16 v[116:119], v[188:191], v[196:199], v[116:119]
	v_mfma_f32_16x16x32_bf16 v[96:99], v[188:191], v[210:213], v[96:99]
	v_mfma_f32_16x16x32_bf16 v[100:103], v[148:151], v[210:213], v[100:103]
	v_mfma_f32_16x16x32_bf16 v[84:87], v[148:151], v[218:221], v[84:87]
	v_mfma_f32_16x16x32_bf16 v[80:83], v[188:191], v[218:221], v[80:83]
	v_mfma_f32_16x16x32_bf16 v[64:67], v[188:191], v[226:229], v[64:67]
	v_mfma_f32_16x16x32_bf16 v[68:71], v[148:151], v[226:229], v[68:71]
	s_setprio 0
	s_barrier
; #define PG8_STAGE(bufoff, gbase, voff) do { _Pragma("unroll") for (int _i = 0; _i < 2; ++_i) \
;         __builtin_amdgcn_global_load_lds((const unsigned*)((const char*)(gbase) + (voff)[_i]), (LAS unsigned*)(lds + (bufoff) + ldsw + _i * 8192), 16, 0, 0); } while (0)
; #define PG8_LDA(dst, b, h) do { _Pragma("unroll") for (int m = 0; m < 4; ++m) _Pragma("unroll") for (int k = 0; k < 2; ++k) dst[m][k] = *(const LAS bf16x8*)(lds + PG8_SA(b, h) + aoff + m * 2048 + k * 1024); } while (0)
; #define PG8_MMA(ai, bj, At, Bt) do { __builtin_amdgcn_s_setprio(3); _Pragma("unroll") for (int m = 0; m < 4; ++m) _Pragma("unroll") for (int n = 0; n < 2; ++n) _Pragma("unroll") for (int k = 0; k < 2; ++k) \
;         acc[ai][bj][m][n] = __builtin_amdgcn_mfma_f32_16x16x32_bf16(Bt[n][k], At[m][k], acc[ai][bj][m][n], 0, 0, 0); __builtin_amdgcn_s_setprio(0); } while (0)
; #define PG8_WAIT_V(n) asm volatile("s_waitcnt vmcnt(" #n ")" ::: "memory")
; #define PG8_WAIT_L(n) asm volatile("s_waitcnt lgkmcnt(" #n ")" ::: "memory")
; #define PG8_BAR __builtin_amdgcn_s_barrier()
; #define PG8_SCHED __builtin_amdgcn_sched_barrier(0)
; template <class Epi, class Sched, bool ALIGN_EPI = false, bool SP2 = false>
; __device__ __forceinline__ void gemm_phase(LAS unsigned char* lds, const Gemm g, const Sched& S, const Epi& E) {
;     ...
;             PG8_LDA(At, 1, 1); PG8_STAGE(PG8_SB(1, 0), b3, voffB); PG8_STAGE(PG8_SB(1, 1), b3 + hsB, voffB); PG8_STAGE(PG8_SA(1, 0), a3, voffA);
;             PG8_WAIT_V(8); PG8_WAIT_L(0); PG8_BAR; PG8_MMA(1, 0, At, B0); PG8_MMA(1, 1, At, B1); PG8_BAR; PG8_SCHED;
	s_add_i32 s26, s74, s31
	v_lshl_add_u64 v[200:201], v[200:201], 0, s[14:15]
	s_mov_b32 m0, s26
	ds_read_b128 v[192:195], v177 offset:49152
	ds_read_b128 v[196:199], v177 offset:50176
	ds_read_b128 v[206:209], v177 offset:51200
	ds_read_b128 v[210:213], v177 offset:52224
	ds_read_b128 v[214:217], v177 offset:53248
	ds_read_b128 v[218:221], v177 offset:54272
	ds_read_b128 v[222:225], v177 offset:55296
	ds_read_b128 v[226:229], v177 offset:56320
	global_load_lds_dwordx4 v[200:201], off
	s_add_i32 m0, s26, 0x2000
	s_add_u32 s24, s24, 0x41080
	v_lshl_add_u64 v[200:201], v[230:231], 0, s[14:15]
	s_addc_u32 s25, s25, 0
	s_add_i32 s26, s75, s31
	global_load_lds_dwordx4 v[200:201], off
	v_lshl_add_u64 v[200:201], s[24:25], 0, v[154:155]
	s_mov_b32 m0, s26
	s_nop 0
	global_load_lds_dwordx4 v[200:201], off
	v_lshl_add_u64 v[200:201], s[24:25], 0, v[158:159]
	s_add_i32 m0, s26, 0x2000
	s_nop 0
	global_load_lds_dwordx4 v[200:201], off
	v_lshl_add_u64 v[200:201], v[232:233], 0, s[14:15]
	s_mov_b32 m0, s42
	s_nop 0
	global_load_lds_dwordx4 v[200:201], off
	v_lshl_add_u64 v[200:201], v[234:235], 0, s[14:15]
	s_mov_b32 m0, s43
	s_nop 0
	global_load_lds_dwordx4 v[200:201], off
	s_waitcnt vmcnt(8)
	s_waitcnt lgkmcnt(0)
	s_barrier
	s_setprio 3
	s_waitcnt lgkmcnt(0)
	v_mfma_f32_16x16x32_bf16 v[60:63], v[112:115], v[192:195], v[60:63]
	v_mfma_f32_16x16x32_bf16 v[56:59], v[136:139], v[192:195], v[56:59]
	v_mfma_f32_16x16x32_bf16 v[40:43], v[136:139], v[206:209], v[40:43]
	v_mfma_f32_16x16x32_bf16 v[44:47], v[112:115], v[206:209], v[44:47]
	v_mfma_f32_16x16x32_bf16 v[28:31], v[112:115], v[214:217], v[28:31]
	v_mfma_f32_16x16x32_bf16 v[24:27], v[136:139], v[214:217], v[24:27]
	v_mfma_f32_16x16x32_bf16 v[8:11], v[136:139], v[222:225], v[8:11]
	v_mfma_f32_16x16x32_bf16 v[12:15], v[112:115], v[222:225], v[12:15]
	v_mfma_f32_16x16x32_bf16 v[60:63], v[132:135], v[196:199], v[60:63]
	v_mfma_f32_16x16x32_bf16 v[56:59], v[140:143], v[196:199], v[56:59]
	v_mfma_f32_16x16x32_bf16 v[40:43], v[140:143], v[210:213], v[40:43]
	v_mfma_f32_16x16x32_bf16 v[44:47], v[132:135], v[210:213], v[44:47]
	v_mfma_f32_16x16x32_bf16 v[28:31], v[132:135], v[218:221], v[28:31]
	v_mfma_f32_16x16x32_bf16 v[24:27], v[140:143], v[218:221], v[24:27]
	v_mfma_f32_16x16x32_bf16 v[8:11], v[140:143], v[226:229], v[8:11]
	v_mfma_f32_16x16x32_bf16 v[12:15], v[132:135], v[226:229], v[12:15]
	s_setprio 0
	s_setprio 3
	v_mfma_f32_16x16x32_bf16 v[52:55], v[144:147], v[192:195], v[52:55]
	v_mfma_f32_16x16x32_bf16 v[48:51], v[184:187], v[192:195], v[48:51]
	v_mfma_f32_16x16x32_bf16 v[32:35], v[184:187], v[206:209], v[32:35]
	v_mfma_f32_16x16x32_bf16 v[36:39], v[144:147], v[206:209], v[36:39]
	v_mfma_f32_16x16x32_bf16 v[20:23], v[144:147], v[214:217], v[20:23]
	v_mfma_f32_16x16x32_bf16 v[16:19], v[184:187], v[214:217], v[16:19]
	v_mfma_f32_16x16x32_bf16 v[0:3], v[184:187], v[222:225], v[0:3]
	v_mfma_f32_16x16x32_bf16 v[4:7], v[144:147], v[222:225], v[4:7]
	v_mfma_f32_16x16x32_bf16 v[52:55], v[148:151], v[196:199], v[52:55]
	v_mfma_f32_16x16x32_bf16 v[48:51], v[188:191], v[196:199], v[48:51]
	v_mfma_f32_16x16x32_bf16 v[32:35], v[188:191], v[210:213], v[32:35]
	v_mfma_f32_16x16x32_bf16 v[36:39], v[148:151], v[210:213], v[36:39]
	v_mfma_f32_16x16x32_bf16 v[20:23], v[148:151], v[218:221], v[20:23]
	v_mfma_f32_16x16x32_bf16 v[16:19], v[188:191], v[218:221], v[16:19]
	v_mfma_f32_16x16x32_bf16 v[0:3], v[188:191], v[226:229], v[0:3]
	v_mfma_f32_16x16x32_bf16 v[4:7], v[148:151], v[226:229], v[4:7]
	s_setprio 0
	s_barrier
	s_add_i32 s73, s73, 2
	s_add_u32 s4, s4, 0x100
	s_addc_u32 s5, s5, 0
	s_add_u32 s71, s71, 0x100
	s_addc_u32 s72, s72, 0
	s_cmp_gt_u32 s73, 61
	s_cbranch_scc0 .LBB0_309
	s_and_b64 vcc, exec, s[16:17]
	s_cbranch_vccz .LBB0_312
	s_barrier

; #define PG8_STAGE(bufoff, gbase, voff) do { _Pragma("unroll") for (int _i = 0; _i < 2; ++_i) \
;         __builtin_amdgcn_global_load_lds((const unsigned*)((const char*)(gbase) + (voff)[_i]), (LAS unsigned*)(lds + (bufoff) + ldsw + _i * 8192), 16, 0, 0); } while (0)
; #define PG8_LDA(dst, b, h) do { _Pragma("unroll") for (int m = 0; m < 4; ++m) _Pragma("unroll") for (int k = 0; k < 2; ++k) dst[m][k] = *(const LAS bf16x8*)(lds + PG8_SA(b, h) + aoff + m * 2048 + k * 1024); } while (0)
; #define PG8_LDB(dst, b, h) do { _Pragma("unroll") for (int n = 0; n < 2; ++n) _Pragma("unroll") for (int k = 0; k < 2; ++k) dst[n][k] = *(const LAS bf16x8*)(lds + PG8_SB(b, h) + boff + n * 2048 + k * 1024); } while (0)
; #define PG8_MMA(ai, bj, At, Bt) do { __builtin_amdgcn_s_setprio(3); _Pragma("unroll") for (int m = 0; m < 4; ++m) _Pragma("unroll") for (int n = 0; n < 2; ++n) _Pragma("unroll") for (int k = 0; k < 2; ++k) \
;         acc[ai][bj][m][n] = __builtin_amdgcn_mfma_f32_16x16x32_bf16(Bt[n][k], At[m][k], acc[ai][bj][m][n], 0, 0, 0); __builtin_amdgcn_s_setprio(0); } while (0)
; #define PG8_WAIT_V(n) asm volatile("s_waitcnt vmcnt(" #n ")" ::: "memory")
; #define PG8_WAIT_L(n) asm volatile("s_waitcnt lgkmcnt(" #n ")" ::: "memory")
; #define PG8_BAR __builtin_amdgcn_s_barrier()
; #define PG8_SCHED __builtin_amdgcn_sched_barrier(0)
; template <class Epi, class Sched, bool ALIGN_EPI = false, bool SP2 = false>
; __device__ __forceinline__ void gemm_phase(LAS unsigned char* lds, const Gemm g, const Sched& S, const Epi& E) {
;     ...
;             PG8_LDB(B0, 0, 0); PG8_LDB(B1, 0, 1); PG8_SCHED; PG8_LDA(At, 0, 0); PG8_STAGE(PG8_SA(1, 1), a1 + hsA, voffA);
;             PG8_WAIT_V(8); PG8_WAIT_L(0); PG8_BAR; PG8_MMA(0, 0, At, B0); PG8_MMA(0, 1, At, B1); PG8_BAR; PG8_SCHED;
;             PG8_LDA(At, 0, 1); PG8_STAGE(PG8_SB(0, 0), b2, voffB); PG8_STAGE(PG8_SB(0, 1), b2 + hsB, voffB); PG8_STAGE(PG8_SA(0, 0), a2, voffA);
;             PG8_WAIT_V(8); PG8_WAIT_L(0); PG8_BAR; PG8_MMA(1, 0, At, B0); PG8_MMA(1, 1, At, B1); PG8_BAR; PG8_SCHED;
.LBB0_350:
	ds_read_b128 v[140:143], v149
	ds_read_b128 v[156:159], v149 offset:1024
	ds_read_b128 v[160:163], v149 offset:2048
	ds_read_b128 v[164:167], v149 offset:3072
	ds_read_b128 v[168:171], v150
	ds_read_b128 v[172:175], v150 offset:1024
	ds_read_b128 v[176:179], v150 offset:2048
	ds_read_b128 v[180:183], v150 offset:3072
	s_add_u32 s16, s14, 0xffbfc080
	s_addc_u32 s17, s15, -1
	s_cmpk_eq_i32 s50, 0xfc
	s_cselect_b32 s21, s5, s17
	s_cselect_b32 s20, s4, s16
	s_cselect_b32 s17, s13, s49
	s_cselect_b32 s16, s12, s48
	v_lshl_add_u64 v[144:145], s[14:15], 0, v[132:133]
	s_add_i32 m0, s26, 0xc000
	ds_read_b128 v[184:187], v151
	ds_read_b128 v[188:191], v151 offset:1024
	ds_read_b128 v[192:195], v151 offset:2048
	ds_read_b128 v[196:199], v151 offset:3072
	ds_read_b128 v[200:203], v151 offset:4096
	ds_read_b128 v[204:207], v151 offset:5120
	ds_read_b128 v[208:211], v151 offset:6144
	ds_read_b128 v[212:215], v151 offset:7168
	global_load_lds_dwordx4 v[144:145], off
	v_lshl_add_u64 v[144:145], s[14:15], 0, v[134:135]
	s_add_i32 m0, s26, 0xe000
	s_nop 0
	global_load_lds_dwordx4 v[144:145], off
	s_waitcnt vmcnt(8)
	s_waitcnt lgkmcnt(0)
	s_barrier
	s_setprio 3
	s_waitcnt lgkmcnt(0)
	v_mfma_f32_16x16x32_bf16 v[124:127], v[140:143], v[184:187], v[124:127]
	v_mfma_f32_16x16x32_bf16 v[120:123], v[160:163], v[184:187], v[120:123]
	v_mfma_f32_16x16x32_bf16 v[104:107], v[160:163], v[192:195], v[104:107]
	v_mfma_f32_16x16x32_bf16 v[108:111], v[140:143], v[192:195], v[108:111]
	v_mfma_f32_16x16x32_bf16 v[92:95], v[140:143], v[200:203], v[92:95]
	v_mfma_f32_16x16x32_bf16 v[88:91], v[160:163], v[200:203], v[88:91]
	v_mfma_f32_16x16x32_bf16 v[72:75], v[160:163], v[208:211], v[72:75]
	v_mfma_f32_16x16x32_bf16 v[76:79], v[140:143], v[208:211], v[76:79]
	v_mfma_f32_16x16x32_bf16 v[124:127], v[156:159], v[188:191], v[124:127]
	v_mfma_f32_16x16x32_bf16 v[120:123], v[164:167], v[188:191], v[120:123]
	v_mfma_f32_16x16x32_bf16 v[104:107], v[164:167], v[196:199], v[104:107]
	v_mfma_f32_16x16x32_bf16 v[108:111], v[156:159], v[196:199], v[108:111]
	v_mfma_f32_16x16x32_bf16 v[92:95], v[156:159], v[204:207], v[92:95]
	v_mfma_f32_16x16x32_bf16 v[88:91], v[164:167], v[204:207], v[88:91]
	v_mfma_f32_16x16x32_bf16 v[72:75], v[164:167], v[212:215], v[72:75]
	v_mfma_f32_16x16x32_bf16 v[76:79], v[156:159], v[212:215], v[76:79]
	s_setprio 0
	s_setprio 3
	v_mfma_f32_16x16x32_bf16 v[116:119], v[168:171], v[184:187], v[116:119]
	v_mfma_f32_16x16x32_bf16 v[112:115], v[176:179], v[184:187], v[112:115]
	v_mfma_f32_16x16x32_bf16 v[96:99], v[176:179], v[192:195], v[96:99]
	v_mfma_f32_16x16x32_bf16 v[100:103], v[168:171], v[192:195], v[100:103]
	v_mfma_f32_16x16x32_bf16 v[84:87], v[168:171], v[200:203], v[84:87]
	v_mfma_f32_16x16x32_bf16 v[80:83], v[176:179], v[200:203], v[80:83]
	v_mfma_f32_16x16x32_bf16 v[64:67], v[176:179], v[208:211], v[64:67]
	v_mfma_f32_16x16x32_bf16 v[68:71], v[168:171], v[208:211], v[68:71]
	v_mfma_f32_16x16x32_bf16 v[116:119], v[172:175], v[188:191], v[116:119]
	v_mfma_f32_16x16x32_bf16 v[112:115], v[180:183], v[188:191], v[112:115]
	v_mfma_f32_16x16x32_bf16 v[96:99], v[180:183], v[196:199], v[96:99]
	v_mfma_f32_16x16x32_bf16 v[100:103], v[172:175], v[196:199], v[100:103]
	v_mfma_f32_16x16x32_bf16 v[84:87], v[172:175], v[204:207], v[84:87]
	v_mfma_f32_16x16x32_bf16 v[80:83], v[180:183], v[204:207], v[80:83]
	v_mfma_f32_16x16x32_bf16 v[64:67], v[180:183], v[212:215], v[64:67]
	v_mfma_f32_16x16x32_bf16 v[68:71], v[172:175], v[212:215], v[68:71]
	s_setprio 0
	s_barrier
	s_add_i32 s51, s41, s25
	v_lshl_add_u64 v[144:145], s[16:17], 0, v[128:129]
	s_mov_b32 m0, s51
	ds_read_b128 v[184:187], v151 offset:16384
	ds_read_b128 v[188:191], v151 offset:17408
	ds_read_b128 v[192:195], v151 offset:18432
	ds_read_b128 v[196:199], v151 offset:19456
	ds_read_b128 v[200:203], v151 offset:20480
	ds_read_b128 v[204:207], v151 offset:21504
	ds_read_b128 v[208:211], v151 offset:22528
	ds_read_b128 v[212:215], v151 offset:23552
	global_load_lds_dwordx4 v[144:145], off
	s_add_i32 m0, s51, 0x2000
	s_add_u32 s52, s16, 0x404000
	v_lshl_add_u64 v[216:217], s[16:17], 0, v[130:131]
	s_addc_u32 s53, s17, 0
	s_add_i32 s51, s42, s25
	global_load_lds_dwordx4 v[216:217], off
	v_lshl_add_u64 v[218:219], s[52:53], 0, v[128:129]
	s_mov_b32 m0, s51
	v_lshl_add_u64 v[220:221], s[20:21], 0, v[130:131]
	global_load_lds_dwordx4 v[218:219], off
	v_lshl_add_u64 v[218:219], s[52:53], 0, v[130:131]
	s_add_i32 m0, s51, 0x2000
	s_nop 0
	global_load_lds_dwordx4 v[218:219], off
	v_lshl_add_u64 v[218:219], s[20:21], 0, v[128:129]
	s_mov_b32 m0, s26
	s_nop 0
	global_load_lds_dwordx4 v[218:219], off
	s_mov_b32 m0, s27
	s_nop 0
	global_load_lds_dwordx4 v[220:221], off
	s_waitcnt vmcnt(8)
	s_waitcnt lgkmcnt(0)
	s_barrier
; #define PG8_STAGE(bufoff, gbase, voff) do { _Pragma("unroll") for (int _i = 0; _i < 2; ++_i) \
;         __builtin_amdgcn_global_load_lds((const unsigned*)((const char*)(gbase) + (voff)[_i]), (LAS unsigned*)(lds + (bufoff) + ldsw + _i * 8192), 16, 0, 0); } while (0)
; #define PG8_LDA(dst, b, h) do { _Pragma("unroll") for (int m = 0; m < 4; ++m) _Pragma("unroll") for (int k = 0; k < 2; ++k) dst[m][k] = *(const LAS bf16x8*)(lds + PG8_SA(b, h) + aoff + m * 2048 + k * 1024); } while (0)
; #define PG8_LDB(dst, b, h) do { _Pragma("unroll") for (int n = 0; n < 2; ++n) _Pragma("unroll") for (int k = 0; k < 2; ++k) dst[n][k] = *(const LAS bf16x8*)(lds + PG8_SB(b, h) + boff + n * 2048 + k * 1024); } while (0)
; #define PG8_MMA(ai, bj, At, Bt) do { __builtin_amdgcn_s_setprio(3); _Pragma("unroll") for (int m = 0; m < 4; ++m) _Pragma("unroll") for (int n = 0; n < 2; ++n) _Pragma("unroll") for (int k = 0; k < 2; ++k) \
;         acc[ai][bj][m][n] = __builtin_amdgcn_mfma_f32_16x16x32_bf16(Bt[n][k], At[m][k], acc[ai][bj][m][n], 0, 0, 0); __builtin_amdgcn_s_setprio(0); } while (0)
; #define PG8_WAIT_V(n) asm volatile("s_waitcnt vmcnt(" #n ")" ::: "memory")
; #define PG8_WAIT_L(n) asm volatile("s_waitcnt lgkmcnt(" #n ")" ::: "memory")
; #define PG8_BAR __builtin_amdgcn_s_barrier()
; #define PG8_SCHED __builtin_amdgcn_sched_barrier(0)
; template <class Epi, class Sched, bool ALIGN_EPI = false, bool SP2 = false>
; __device__ __forceinline__ void gemm_phase(LAS unsigned char* lds, const Gemm g, const Sched& S, const Epi& E) {
;     ...
;             PG8_WAIT_V(8); PG8_WAIT_L(0); PG8_BAR; PG8_MMA(1, 0, At, B0); PG8_MMA(1, 1, At, B1); PG8_BAR; PG8_SCHED;
;             PG8_LDB(B0, 1, 0); PG8_LDB(B1, 1, 1); PG8_SCHED; PG8_LDA(At, 1, 0); PG8_STAGE(PG8_SA(0, 1), a2 + hsA, voffA);
;             PG8_WAIT_V(8); PG8_WAIT_L(0); PG8_BAR; PG8_MMA(0, 0, At, B0); PG8_MMA(0, 1, At, B1); PG8_BAR; PG8_SCHED;
	s_setprio 3
	s_waitcnt lgkmcnt(0)
	v_mfma_f32_16x16x32_bf16 v[60:63], v[140:143], v[184:187], v[60:63]
	v_mfma_f32_16x16x32_bf16 v[56:59], v[160:163], v[184:187], v[56:59]
	v_mfma_f32_16x16x32_bf16 v[40:43], v[160:163], v[192:195], v[40:43]
	v_mfma_f32_16x16x32_bf16 v[44:47], v[140:143], v[192:195], v[44:47]
	v_mfma_f32_16x16x32_bf16 v[28:31], v[140:143], v[200:203], v[28:31]
	v_mfma_f32_16x16x32_bf16 v[24:27], v[160:163], v[200:203], v[24:27]
	v_mfma_f32_16x16x32_bf16 v[8:11], v[160:163], v[208:211], v[8:11]
	v_mfma_f32_16x16x32_bf16 v[12:15], v[140:143], v[208:211], v[12:15]
	v_mfma_f32_16x16x32_bf16 v[60:63], v[156:159], v[188:191], v[60:63]
	v_mfma_f32_16x16x32_bf16 v[56:59], v[164:167], v[188:191], v[56:59]
	v_mfma_f32_16x16x32_bf16 v[40:43], v[164:167], v[196:199], v[40:43]
	v_mfma_f32_16x16x32_bf16 v[44:47], v[156:159], v[196:199], v[44:47]
	v_mfma_f32_16x16x32_bf16 v[28:31], v[156:159], v[204:207], v[28:31]
	v_mfma_f32_16x16x32_bf16 v[24:27], v[164:167], v[204:207], v[24:27]
	v_mfma_f32_16x16x32_bf16 v[8:11], v[164:167], v[212:215], v[8:11]
	v_mfma_f32_16x16x32_bf16 v[12:15], v[156:159], v[212:215], v[12:15]
	s_setprio 0
	s_setprio 3
	v_mfma_f32_16x16x32_bf16 v[52:55], v[168:171], v[184:187], v[52:55]
	v_mfma_f32_16x16x32_bf16 v[48:51], v[176:179], v[184:187], v[48:51]
	v_mfma_f32_16x16x32_bf16 v[32:35], v[176:179], v[192:195], v[32:35]
	v_mfma_f32_16x16x32_bf16 v[36:39], v[168:171], v[192:195], v[36:39]
	v_mfma_f32_16x16x32_bf16 v[20:23], v[168:171], v[200:203], v[20:23]
	v_mfma_f32_16x16x32_bf16 v[16:19], v[176:179], v[200:203], v[16:19]
	v_mfma_f32_16x16x32_bf16 v[0:3], v[176:179], v[208:211], v[0:3]
	v_mfma_f32_16x16x32_bf16 v[4:7], v[168:171], v[208:211], v[4:7]
	v_mfma_f32_16x16x32_bf16 v[52:55], v[172:175], v[188:191], v[52:55]
	v_mfma_f32_16x16x32_bf16 v[48:51], v[180:183], v[188:191], v[48:51]
	v_mfma_f32_16x16x32_bf16 v[32:35], v[180:183], v[196:199], v[32:35]
	v_mfma_f32_16x16x32_bf16 v[36:39], v[172:175], v[196:199], v[36:39]
	v_mfma_f32_16x16x32_bf16 v[20:23], v[172:175], v[204:207], v[20:23]
	v_mfma_f32_16x16x32_bf16 v[16:19], v[180:183], v[204:207], v[16:19]
	v_mfma_f32_16x16x32_bf16 v[0:3], v[180:183], v[212:215], v[0:3]
	v_mfma_f32_16x16x32_bf16 v[4:7], v[172:175], v[212:215], v[4:7]
	s_setprio 0
	s_barrier
	s_add_i32 s51, 0, 0x18000
	v_add_u32_e32 v155, s51, v146
	s_add_i32 s52, 0, 0x1c000
	ds_read_b128 v[140:143], v155
	ds_read_b128 v[156:159], v155 offset:1024
	ds_read_b128 v[160:163], v155 offset:2048
	ds_read_b128 v[164:167], v155 offset:3072
	v_add_u32_e32 v155, s52, v146
	ds_read_b128 v[168:171], v155
	ds_read_b128 v[172:175], v155 offset:1024
	ds_read_b128 v[176:179], v155 offset:2048
	ds_read_b128 v[180:183], v155 offset:3072
	s_add_u32 s20, s20, 0x404000
	s_addc_u32 s21, s21, 0
	s_mov_b32 m0, s30
	v_lshl_add_u64 v[222:223], s[20:21], 0, v[128:129]
	ds_read_b128 v[184:187], v151 offset:32768
	ds_read_b128 v[188:191], v151 offset:33792
	ds_read_b128 v[192:195], v151 offset:34816
	ds_read_b128 v[196:199], v151 offset:35840
	ds_read_b128 v[200:203], v151 offset:36864
	ds_read_b128 v[204:207], v151 offset:37888
	ds_read_b128 v[208:211], v151 offset:38912
	ds_read_b128 v[212:215], v151 offset:39936
	global_load_lds_dwordx4 v[222:223], off
	v_lshl_add_u64 v[222:223], s[20:21], 0, v[130:131]
	s_mov_b32 m0, s31
	s_nop 0
	global_load_lds_dwordx4 v[222:223], off
	s_waitcnt vmcnt(8)
	s_waitcnt lgkmcnt(0)
	s_barrier
	s_setprio 3
	s_waitcnt lgkmcnt(0)
	v_mfma_f32_16x16x32_bf16 v[124:127], v[140:143], v[184:187], v[124:127]
	v_mfma_f32_16x16x32_bf16 v[120:123], v[160:163], v[184:187], v[120:123]
	v_mfma_f32_16x16x32_bf16 v[104:107], v[160:163], v[192:195], v[104:107]
	v_mfma_f32_16x16x32_bf16 v[108:111], v[140:143], v[192:195], v[108:111]
	v_mfma_f32_16x16x32_bf16 v[92:95], v[140:143], v[200:203], v[92:95]
	v_mfma_f32_16x16x32_bf16 v[88:91], v[160:163], v[200:203], v[88:91]
	v_mfma_f32_16x16x32_bf16 v[72:75], v[160:163], v[208:211], v[72:75]
	v_mfma_f32_16x16x32_bf16 v[76:79], v[140:143], v[208:211], v[76:79]
	v_mfma_f32_16x16x32_bf16 v[124:127], v[156:159], v[188:191], v[124:127]
	v_mfma_f32_16x16x32_bf16 v[120:123], v[164:167], v[188:191], v[120:123]
	v_mfma_f32_16x16x32_bf16 v[104:107], v[164:167], v[196:199], v[104:107]
	v_mfma_f32_16x16x32_bf16 v[108:111], v[156:159], v[196:199], v[108:111]
	v_mfma_f32_16x16x32_bf16 v[92:95], v[156:159], v[204:207], v[92:95]
	v_mfma_f32_16x16x32_bf16 v[88:91], v[164:167], v[204:207], v[88:91]
	v_mfma_f32_16x16x32_bf16 v[72:75], v[164:167], v[212:215], v[72:75]
	v_mfma_f32_16x16x32_bf16 v[76:79], v[156:159], v[212:215], v[76:79]
	s_setprio 0
	s_setprio 3
	v_mfma_f32_16x16x32_bf16 v[116:119], v[168:171], v[184:187], v[116:119]
	v_mfma_f32_16x16x32_bf16 v[112:115], v[176:179], v[184:187], v[112:115]
	v_mfma_f32_16x16x32_bf16 v[96:99], v[176:179], v[192:195], v[96:99]
	v_mfma_f32_16x16x32_bf16 v[100:103], v[168:171], v[192:195], v[100:103]
	v_mfma_f32_16x16x32_bf16 v[84:87], v[168:171], v[200:203], v[84:87]
	v_mfma_f32_16x16x32_bf16 v[80:83], v[176:179], v[200:203], v[80:83]
	v_mfma_f32_16x16x32_bf16 v[64:67], v[176:179], v[208:211], v[64:67]
	v_mfma_f32_16x16x32_bf16 v[68:71], v[168:171], v[208:211], v[68:71]
	v_mfma_f32_16x16x32_bf16 v[116:119], v[172:175], v[188:191], v[116:119]
	v_mfma_f32_16x16x32_bf16 v[112:115], v[180:183], v[188:191], v[112:115]
	v_mfma_f32_16x16x32_bf16 v[96:99], v[180:183], v[196:199], v[96:99]
	v_mfma_f32_16x16x32_bf16 v[100:103], v[172:175], v[196:199], v[100:103]
	v_mfma_f32_16x16x32_bf16 v[84:87], v[172:175], v[204:207], v[84:87]
	v_mfma_f32_16x16x32_bf16 v[80:83], v[180:183], v[204:207], v[80:83]
	v_mfma_f32_16x16x32_bf16 v[64:67], v[180:183], v[212:215], v[64:67]
	v_mfma_f32_16x16x32_bf16 v[68:71], v[172:175], v[212:215], v[68:71]
	s_setprio 0
	s_barrier
; #define PG8_STAGE(bufoff, gbase, voff) do { _Pragma("unroll") for (int _i = 0; _i < 2; ++_i) \
;         __builtin_amdgcn_global_load_lds((const unsigned*)((const char*)(gbase) + (voff)[_i]), (LAS unsigned*)(lds + (bufoff) + ldsw + _i * 8192), 16, 0, 0); } while (0)
; #define PG8_LDA(dst, b, h) do { _Pragma("unroll") for (int m = 0; m < 4; ++m) _Pragma("unroll") for (int k = 0; k < 2; ++k) dst[m][k] = *(const LAS bf16x8*)(lds + PG8_SA(b, h) + aoff + m * 2048 + k * 1024); } while (0)
; #define PG8_MMA(ai, bj, At, Bt) do { __builtin_amdgcn_s_setprio(3); _Pragma("unroll") for (int m = 0; m < 4; ++m) _Pragma("unroll") for (int n = 0; n < 2; ++n) _Pragma("unroll") for (int k = 0; k < 2; ++k) \
;         acc[ai][bj][m][n] = __builtin_amdgcn_mfma_f32_16x16x32_bf16(Bt[n][k], At[m][k], acc[ai][bj][m][n], 0, 0, 0); __builtin_amdgcn_s_setprio(0); } while (0)
; #define PG8_WAIT_V(n) asm volatile("s_waitcnt vmcnt(" #n ")" ::: "memory")
; #define PG8_WAIT_L(n) asm volatile("s_waitcnt lgkmcnt(" #n ")" ::: "memory")
; #define PG8_BAR __builtin_amdgcn_s_barrier()
; #define PG8_SCHED __builtin_amdgcn_sched_barrier(0)
; template <class Epi, class Sched, bool ALIGN_EPI = false, bool SP2 = false>
; __device__ __forceinline__ void gemm_phase(LAS unsigned char* lds, const Gemm g, const Sched& S, const Epi& E) {
;     ...
;             PG8_LDA(At, 1, 1); PG8_STAGE(PG8_SB(1, 0), b3, voffB); PG8_STAGE(PG8_SB(1, 1), b3 + hsB, voffB); PG8_STAGE(PG8_SA(1, 0), a3, voffA);
;             PG8_WAIT_V(8); PG8_WAIT_L(0); PG8_BAR; PG8_MMA(1, 0, At, B0); PG8_MMA(1, 1, At, B1); PG8_BAR; PG8_SCHED;
	s_add_i32 s20, s51, s25
	v_lshl_add_u64 v[144:145], v[144:145], 0, s[8:9]
	s_mov_b32 m0, s20
	ds_read_b128 v[184:187], v151 offset:49152
	ds_read_b128 v[188:191], v151 offset:50176
	ds_read_b128 v[192:195], v151 offset:51200
	ds_read_b128 v[196:199], v151 offset:52224
	ds_read_b128 v[200:203], v151 offset:53248
	ds_read_b128 v[204:207], v151 offset:54272
	ds_read_b128 v[208:211], v151 offset:55296
	ds_read_b128 v[212:215], v151 offset:56320
	global_load_lds_dwordx4 v[144:145], off
	s_add_i32 m0, s20, 0x2000
	s_add_u32 s16, s16, 0x404080
	v_lshl_add_u64 v[144:145], v[216:217], 0, s[8:9]
	s_addc_u32 s17, s17, 0
	s_add_i32 s20, s52, s25
	global_load_lds_dwordx4 v[144:145], off
	v_lshl_add_u64 v[144:145], s[16:17], 0, v[128:129]
	s_mov_b32 m0, s20
	s_nop 0
	global_load_lds_dwordx4 v[144:145], off
	v_lshl_add_u64 v[144:145], s[16:17], 0, v[130:131]
	s_add_i32 m0, s20, 0x2000
	s_nop 0
	global_load_lds_dwordx4 v[144:145], off
	v_lshl_add_u64 v[144:145], v[218:219], 0, s[8:9]
	s_mov_b32 m0, s33
	s_nop 0
	global_load_lds_dwordx4 v[144:145], off
	v_lshl_add_u64 v[144:145], v[220:221], 0, s[8:9]
	s_mov_b32 m0, s38
	s_nop 0
	global_load_lds_dwordx4 v[144:145], off
	s_waitcnt vmcnt(8)
	s_waitcnt lgkmcnt(0)
	s_barrier
	s_setprio 3
	s_waitcnt lgkmcnt(0)
	v_mfma_f32_16x16x32_bf16 v[60:63], v[140:143], v[184:187], v[60:63]
	v_mfma_f32_16x16x32_bf16 v[56:59], v[160:163], v[184:187], v[56:59]
	v_mfma_f32_16x16x32_bf16 v[40:43], v[160:163], v[192:195], v[40:43]
	v_mfma_f32_16x16x32_bf16 v[44:47], v[140:143], v[192:195], v[44:47]
	v_mfma_f32_16x16x32_bf16 v[28:31], v[140:143], v[200:203], v[28:31]
	v_mfma_f32_16x16x32_bf16 v[24:27], v[160:163], v[200:203], v[24:27]
	v_mfma_f32_16x16x32_bf16 v[8:11], v[160:163], v[208:211], v[8:11]
	v_mfma_f32_16x16x32_bf16 v[12:15], v[140:143], v[208:211], v[12:15]
	v_mfma_f32_16x16x32_bf16 v[60:63], v[156:159], v[188:191], v[60:63]
	v_mfma_f32_16x16x32_bf16 v[56:59], v[164:167], v[188:191], v[56:59]
	v_mfma_f32_16x16x32_bf16 v[40:43], v[164:167], v[196:199], v[40:43]
	v_mfma_f32_16x16x32_bf16 v[44:47], v[156:159], v[196:199], v[44:47]
	v_mfma_f32_16x16x32_bf16 v[28:31], v[156:159], v[204:207], v[28:31]
	v_mfma_f32_16x16x32_bf16 v[24:27], v[164:167], v[204:207], v[24:27]
	v_mfma_f32_16x16x32_bf16 v[8:11], v[164:167], v[212:215], v[8:11]
	v_mfma_f32_16x16x32_bf16 v[12:15], v[156:159], v[212:215], v[12:15]
	s_setprio 0
	s_setprio 3
	v_mfma_f32_16x16x32_bf16 v[52:55], v[168:171], v[184:187], v[52:55]
	v_mfma_f32_16x16x32_bf16 v[48:51], v[176:179], v[184:187], v[48:51]
	v_mfma_f32_16x16x32_bf16 v[32:35], v[176:179], v[192:195], v[32:35]
	v_mfma_f32_16x16x32_bf16 v[36:39], v[168:171], v[192:195], v[36:39]
	v_mfma_f32_16x16x32_bf16 v[20:23], v[168:171], v[200:203], v[20:23]
	v_mfma_f32_16x16x32_bf16 v[16:19], v[176:179], v[200:203], v[16:19]
	v_mfma_f32_16x16x32_bf16 v[0:3], v[176:179], v[208:211], v[0:3]
	v_mfma_f32_16x16x32_bf16 v[4:7], v[168:171], v[208:211], v[4:7]
	v_mfma_f32_16x16x32_bf16 v[52:55], v[172:175], v[188:191], v[52:55]
	v_mfma_f32_16x16x32_bf16 v[48:51], v[180:183], v[188:191], v[48:51]
	v_mfma_f32_16x16x32_bf16 v[32:35], v[180:183], v[196:199], v[32:35]
	v_mfma_f32_16x16x32_bf16 v[36:39], v[172:175], v[196:199], v[36:39]
	v_mfma_f32_16x16x32_bf16 v[20:23], v[172:175], v[204:207], v[20:23]
	v_mfma_f32_16x16x32_bf16 v[16:19], v[180:183], v[204:207], v[16:19]
	v_mfma_f32_16x16x32_bf16 v[0:3], v[180:183], v[212:215], v[0:3]
	v_mfma_f32_16x16x32_bf16 v[4:7], v[172:175], v[212:215], v[4:7]
	s_setprio 0
	s_barrier
	s_add_i32 s50, s50, 2
	s_add_u32 s14, s14, 0x100
	s_addc_u32 s15, s15, 0
	s_add_u32 s48, s48, 0x100
	s_addc_u32 s49, s49, 0
	s_cmpk_gt_u32 s50, 0xfd
	s_cbranch_scc0 .LBB0_350
	s_and_b64 vcc, exec, s[10:11]
	s_cbranch_vccz .LBB0_353
	s_barrier

; __global__ void __launch_bounds__(NWAVES * 64, 2) fwd_mega(Args args) {
	.amdhsa_kernel _Z8fwd_mega4Args
		.amdhsa_group_segment_fixed_size 0
		.amdhsa_private_segment_fixed_size 0
		.amdhsa_kernarg_size 408
		.amdhsa_user_sgpr_count 2
		.amdhsa_user_sgpr_dispatch_ptr 0
		.amdhsa_user_sgpr_queue_ptr 0
		.amdhsa_user_sgpr_kernarg_segment_ptr 1
		.amdhsa_user_sgpr_dispatch_id 0
		.amdhsa_user_sgpr_kernarg_preload_length 0
		.amdhsa_user_sgpr_kernarg_preload_offset 0
		.amdhsa_user_sgpr_private_segment_size 0
		.amdhsa_uses_dynamic_stack 0
		.amdhsa_enable_private_segment 0
		.amdhsa_system_sgpr_workgroup_id_x 1
		.amdhsa_system_sgpr_workgroup_id_y 0
		.amdhsa_system_sgpr_workgroup_id_z 0
		.amdhsa_system_sgpr_workgroup_info 0
		.amdhsa_system_vgpr_workitem_id 2
		.amdhsa_next_free_vgpr 242
		.amdhsa_next_free_sgpr 99
		.amdhsa_accum_offset 244
		.amdhsa_reserve_vcc 1
		.amdhsa_float_round_mode_32 0
		.amdhsa_float_round_mode_16_64 0
		.amdhsa_float_denorm_mode_32 3
		.amdhsa_float_denorm_mode_16_64 3
		.amdhsa_dx10_clamp 1
		.amdhsa_ieee_mode 1
		.amdhsa_fp16_overflow 0
		.amdhsa_tg_split 0
		.amdhsa_exception_fp_ieee_invalid_op 0
		.amdhsa_exception_fp_denorm_src 0
		.amdhsa_exception_fp_ieee_div_zero 0
		.amdhsa_exception_fp_ieee_overflow 0
		.amdhsa_exception_fp_ieee_underflow 0
		.amdhsa_exception_fp_ieee_inexact 0
		.amdhsa_exception_int_div_zero 0
	.end_amdhsa_kernel

; __global__ void __launch_bounds__(NWAVES * 64, 2) fwd_mega(Args args) {
amdhsa.kernels:
  - .agpr_count:     0
    .args:
      - .offset:         0
        .size:           152
        .value_kind:     by_value
      - .offset:         152
        .size:           4
        .value_kind:     hidden_block_count_x
      - .offset:         156
        .size:           4
        .value_kind:     hidden_block_count_y
      - .offset:         160
        .size:           4
        .value_kind:     hidden_block_count_z
      - .offset:         164
        .size:           2
        .value_kind:     hidden_group_size_x
      - .offset:         166
        .size:           2
        .value_kind:     hidden_group_size_y
      - .offset:         168
        .size:           2
        .value_kind:     hidden_group_size_z
      - .offset:         170
        .size:           2
        .value_kind:     hidden_remainder_x
      - .offset:         172
        .size:           2
        .value_kind:     hidden_remainder_y
      - .offset:         174
        .size:           2
        .value_kind:     hidden_remainder_z
      - .offset:         192
        .size:           8
        .value_kind:     hidden_global_offset_x
      - .offset:         200
        .size:           8
        .value_kind:     hidden_global_offset_y
      - .offset:         208
        .size:           8
        .value_kind:     hidden_global_offset_z
      - .offset:         216
        .size:           2
        .value_kind:     hidden_grid_dims
      - .offset:         240
        .size:           8
        .value_kind:     hidden_multigrid_sync_arg
      - .offset:         272
        .size:           4
        .value_kind:     hidden_dynamic_lds_size
    .group_segment_fixed_size: 0
    .kernarg_segment_align: 8
    .kernarg_segment_size: 408
    .language:       OpenCL C
    .language_version:
      - 2
      - 0
    .max_flat_workgroup_size: 512
    .name:           _Z8fwd_mega4Args
    .private_segment_fixed_size: 0
    .sgpr_count:     105
    .sgpr_spill_count: 0
    .symbol:         _Z8fwd_mega4Args.kd
    .uniform_work_group_size: 1
    .uses_dynamic_stack: false
    .vgpr_count:     242
    .vgpr_spill_count: 0
    .wavefront_size: 64
